# in-projection and gate epilogues: the two cross-lane adds of the row sum-of-squares by v_permlane16_swap and v_permlane32_swap instead of two ds_bpermute round trips (same pairing order)
# speedup vs baseline: 1.0060x; 1.0060x over previous
; __device__ __forceinline__ float sigmoid_f(float x) { return __builtin_amdgcn_rcpf(1.0f + __builtin_amdgcn_exp2f(-1.4426950409f * x)); }
; __device__ __forceinline__ u32x4 pack8(const f32x4& v0, const f32x4& v1) { u32x4 w; w.x = cvt_pk_bf16(v0[0], v0[1]); w.y = cvt_pk_bf16(v0[2], v0[3]); w.z = cvt_pk_bf16(v1[0], v1[1]); w.w = cvt_pk_bf16(v1[2], v1[3]); return w; }
; __device__ __forceinline__ float row_rstd(const float* rss, long row, int fq) {
;     const f32x4 p = *(const f32x4*)(rss + row * 16 + fq * 4); float s = (p[0] + p[1]) + (p[2] + p[3]); s += __shfl_xor(s, 16); s += __shfl_xor(s, 32);
;     return rsqrtf(s * (1.0f / 1024.0f) + 1e-6f);
;     __device__ __forceinline__ void operator()(const f32x4 (&acc)[2][2][4][2], const Unit& u, int wr, int wc, int fr, int fq) const {
;         const int t = u.pn >> 2, row0 = u.pm * BM + wr * 64 + fr, col0 = (u.pn & 3) * BM + wc * 32 + 8 * fq;
;         bf16_t* base = t ? GB : GA;
; #pragma unroll
;         for (int ai = 0; ai < 2; ++ai)
; #pragma unroll
;             for (int m = 0; m < 4; ++m) { bf16_t* rowp = base + (size_t)(row0 + ai * HALF + m * 16) * 1024 + col0; const float rn = row_rstd(rss, row0 + ai * HALF + m * 16, fq);
; #pragma unroll
;                 for (int bj = 0; bj < 2; ++bj) { f32x4 v0 = acc[ai][bj][m][0] * rn, v1 = acc[ai][bj][m][1] * rn;
; #pragma unroll
;                     for (int j = 0; j < 4; ++j) { v0[j] = sigmoid_f(v0[j]); v1[j] = sigmoid_f(v1[j]); }
;                     *(u32x4*)(rowp + bj * HALF) = pack8(v0, v1); } }
.LBB0_193:
	s_lshl_b32 s9, s31, 8
	s_and_b32 s9, s9, 0x300
	v_or_b32_e32 v143, s9, v148
	v_cmp_lt_i32_e32 vcc, v251, v246
	v_lshlrev_b32_e32 v208, 1, v143
	v_lshl_add_u32 v142, s46, 8, v146
	v_cndmask_b32_e32 v143, v245, v251, vcc
	v_cmp_lt_i32_e32 vcc, v252, v246
	s_cmp_lt_u32 s31, 4
	v_lshlrev_b32_e32 v150, 2, v143
	v_cndmask_b32_e32 v143, v245, v252, vcc
	s_cselect_b32 s47, s43, s27
	s_cselect_b32 s46, s42, s26
	v_lshlrev_b32_e32 v151, 2, v143
	v_ashrrev_i32_e32 v143, 31, v142
	v_lshl_add_u64 v[144:145], s[46:47], 0, v[208:209]
	v_lshlrev_b64 v[152:153], 11, v[142:143]
	v_lshl_add_u64 v[156:157], v[144:145], 0, v[152:153]
	v_lshlrev_b64 v[152:153], 6, v[142:143]
	v_lshl_add_u64 v[152:153], v[136:137], 0, v[152:153]
	v_mov_b32_e32 v190, v152
	v_mov_b32_e32 v191, v153
	v_add_co_u32_e32 v188, vcc, 0x2000, v152
	s_nop 1
	v_addc_co_u32_e32 v189, vcc, 0, v153, vcc
	global_load_dwordx4 v[152:155], v[152:153], off
	global_load_dwordx4 v[160:163], v[190:191], off offset:1024
	global_load_dwordx4 v[164:167], v[190:191], off offset:2048
	global_load_dwordx4 v[168:171], v[190:191], off offset:3072
	global_load_dwordx4 v[172:175], v[188:189], off
	global_load_dwordx4 v[176:179], v[188:189], off offset:1024
	global_load_dwordx4 v[180:183], v[188:189], off offset:2048
	global_load_dwordx4 v[184:187], v[188:189], off offset:3072
	s_mov_b64 s[46:47], -1
	s_waitcnt vmcnt(7)
	v_mov_b32_e32 v158, v153
	v_mov_b32_e32 v159, v154
	v_mov_b32_e32 v153, v155
	v_pk_add_f32 v[152:153], v[158:159], v[152:153]
	s_nop 0
	v_add_f32_e32 v143, v152, v153
	v_mov_b32_e32 v152, v143
	s_nop 1
	v_permlane16_swap_b32_e32 v143, v152
	s_waitcnt lgkmcnt(0)
	v_add_f32_e32 v143, v143, v152
	v_mov_b32_e32 v152, v143
	s_nop 1
	v_permlane32_swap_b32_e32 v143, v152
	s_waitcnt lgkmcnt(0)
	v_add_f32_e32 v143, v143, v152
	v_fmamk_f32 v143, v143, 0x3a800000, v210
	v_cmp_gt_f32_e32 vcc, s39, v143
	v_mul_f32_e32 v152, 0x4b800000, v143
	s_nop 0
	v_cndmask_b32_e32 v143, v143, v152, vcc
	v_rsq_f32_e32 v143, v143
	s_nop 0
	v_mul_f32_e32 v152, 0x45800000, v143
	v_cndmask_b32_e32 v152, v143, v152, vcc
	v_pk_mul_f32 v[122:123], v[122:123], v[152:153] op_sel_hi:[1,0]
	v_pk_mul_f32 v[120:121], v[120:121], v[152:153] op_sel_hi:[1,0]
	v_mul_f32_e32 v122, 0xbfb8aa3b, v122
	v_mul_f32_e32 v120, 0xbfb8aa3b, v120
	v_mul_f32_e32 v121, 0xbfb8aa3b, v121
	v_exp_f32_e32 v120, v120
	v_exp_f32_e32 v121, v121
	v_exp_f32_e32 v122, v122
	v_pk_mul_f32 v[126:127], v[126:127], v[152:153] op_sel_hi:[1,0]
	v_pk_mul_f32 v[124:125], v[124:125], v[152:153] op_sel_hi:[1,0]
	v_add_f32_e32 v120, 1.0, v120
	v_add_f32_e32 v121, 1.0, v121
	v_add_f32_e32 v122, 1.0, v122
	v_mul_f32_e32 v124, 0xbfb8aa3b, v124
	v_rcp_f32_e32 v143, v120
	v_mul_f32_e32 v120, 0xbfb8aa3b, v125
	v_rcp_f32_e32 v125, v121
	v_mul_f32_e32 v121, 0xbfb8aa3b, v126
	v_rcp_f32_e32 v126, v122
	v_mul_f32_e32 v122, 0xbfb8aa3b, v127
	v_mul_f32_e32 v123, 0xbfb8aa3b, v123
	v_exp_f32_e32 v124, v124
	v_exp_f32_e32 v120, v120
	v_exp_f32_e32 v121, v121
	v_exp_f32_e32 v122, v122
	v_exp_f32_e32 v123, v123
	v_pk_mul_f32 v[114:115], v[114:115], v[152:153] op_sel_hi:[1,0]
	v_pk_mul_f32 v[112:113], v[112:113], v[152:153] op_sel_hi:[1,0]
	v_add_f32_e32 v124, 1.0, v124
	v_add_f32_e32 v120, 1.0, v120
	v_add_f32_e32 v121, 1.0, v121
	v_add_f32_e32 v122, 1.0, v122
	v_add_f32_e32 v123, 1.0, v123
	v_mul_f32_e32 v112, 0xbfb8aa3b, v112
	v_mul_f32_e32 v113, 0xbfb8aa3b, v113
	v_mul_f32_e32 v114, 0xbfb8aa3b, v114
	v_rcp_f32_e32 v124, v124
	v_rcp_f32_e32 v120, v120
	v_rcp_f32_e32 v121, v121
	v_rcp_f32_e32 v122, v122
	v_rcp_f32_e32 v123, v123
	v_exp_f32_e32 v112, v112
	v_exp_f32_e32 v113, v113
	v_exp_f32_e32 v114, v114
	v_cvt_pk_bf16_f32 v120, v124, v120
	v_cvt_pk_bf16_f32 v121, v121, v122
	v_cvt_pk_bf16_f32 v122, v143, v125
	v_cvt_pk_bf16_f32 v123, v126, v123
	v_pk_mul_f32 v[118:119], v[118:119], v[152:153] op_sel_hi:[1,0]
	v_pk_mul_f32 v[116:117], v[116:117], v[152:153] op_sel_hi:[1,0]
	v_add_f32_e32 v112, 1.0, v112
	v_add_f32_e32 v113, 1.0, v113
	v_add_f32_e32 v114, 1.0, v114
	global_store_dwordx4 v[156:157], v[120:123], off
	v_mul_f32_e32 v116, 0xbfb8aa3b, v116
	v_mul_f32_e32 v115, 0xbfb8aa3b, v115
	v_rcp_f32_e32 v120, v112
	v_mul_f32_e32 v112, 0xbfb8aa3b, v117
	v_rcp_f32_e32 v117, v113
	v_mul_f32_e32 v113, 0xbfb8aa3b, v118
	v_rcp_f32_e32 v118, v114
	v_mul_f32_e32 v114, 0xbfb8aa3b, v119
	v_exp_f32_e32 v116, v116
	v_exp_f32_e32 v112, v112
	v_exp_f32_e32 v113, v113
	v_exp_f32_e32 v114, v114
	v_exp_f32_e32 v115, v115
	v_add_f32_e32 v116, 1.0, v116
	v_add_f32_e32 v112, 1.0, v112
	v_add_f32_e32 v113, 1.0, v113
	v_add_f32_e32 v114, 1.0, v114
	v_add_f32_e32 v115, 1.0, v115
	v_rcp_f32_e32 v116, v116
	v_rcp_f32_e32 v112, v112
	v_rcp_f32_e32 v113, v113
	v_rcp_f32_e32 v114, v114
	v_rcp_f32_e32 v115, v115
	v_cvt_pk_bf16_f32 v112, v116, v112
	v_cvt_pk_bf16_f32 v113, v113, v114
	v_cvt_pk_bf16_f32 v114, v120, v117
	v_cvt_pk_bf16_f32 v115, v118, v115
	global_store_dwordx4 v[156:157], v[112:115], off offset:256
	s_nop 1
	v_or_b32_e32 v114, 16, v142
	v_ashrrev_i32_e32 v115, 31, v114
	v_lshlrev_b64 v[112:113], 11, v[114:115]
	v_lshlrev_b64 v[114:115], 6, v[114:115]
	v_lshl_add_u64 v[112:113], v[144:145], 0, v[112:113]
	s_waitcnt vmcnt(8)
	v_mov_b32_e32 v118, v161
	v_mov_b32_e32 v119, v162
	v_mov_b32_e32 v115, v163
	v_mov_b32_e32 v114, v160
	v_pk_add_f32 v[114:115], v[118:119], v[114:115]
	s_nop 0
	v_add_f32_e32 v114, v114, v115
	v_mov_b32_e32 v115, v114
	s_nop 1
	v_permlane16_swap_b32_e32 v114, v115
	s_waitcnt lgkmcnt(0)
	v_add_f32_e32 v114, v114, v115
	v_mov_b32_e32 v115, v114
	s_nop 1
	v_permlane32_swap_b32_e32 v114, v115
	s_waitcnt lgkmcnt(0)
; __device__ __forceinline__ float sigmoid_f(float x) { return __builtin_amdgcn_rcpf(1.0f + __builtin_amdgcn_exp2f(-1.4426950409f * x)); }
; __device__ __forceinline__ u32x4 pack8(const f32x4& v0, const f32x4& v1) { u32x4 w; w.x = cvt_pk_bf16(v0[0], v0[1]); w.y = cvt_pk_bf16(v0[2], v0[3]); w.z = cvt_pk_bf16(v1[0], v1[1]); w.w = cvt_pk_bf16(v1[2], v1[3]); return w; }
; __device__ __forceinline__ float row_rstd(const float* rss, long row, int fq) {
;     const f32x4 p = *(const f32x4*)(rss + row * 16 + fq * 4); float s = (p[0] + p[1]) + (p[2] + p[3]); s += __shfl_xor(s, 16); s += __shfl_xor(s, 32);
;     return rsqrtf(s * (1.0f / 1024.0f) + 1e-6f);
;     __device__ __forceinline__ void operator()(const f32x4 (&acc)[2][2][4][2], const Unit& u, int wr, int wc, int fr, int fq) const {
;     ...
;             for (int m = 0; m < 4; ++m) { bf16_t* rowp = base + (size_t)(row0 + ai * HALF + m * 16) * 1024 + col0; const float rn = row_rstd(rss, row0 + ai * HALF + m * 16, fq);
; #pragma unroll
;                 for (int bj = 0; bj < 2; ++bj) { f32x4 v0 = acc[ai][bj][m][0] * rn, v1 = acc[ai][bj][m][1] * rn;
; #pragma unroll
;                     for (int j = 0; j < 4; ++j) { v0[j] = sigmoid_f(v0[j]); v1[j] = sigmoid_f(v1[j]); }
;                     *(u32x4*)(rowp + bj * HALF) = pack8(v0, v1); } }
	v_add_f32_e32 v114, v114, v115
	v_fmamk_f32 v114, v114, 0x3a800000, v210
	v_cmp_gt_f32_e32 vcc, s39, v114
	v_mul_f32_e32 v115, 0x4b800000, v114
	s_nop 0
	v_cndmask_b32_e32 v114, v114, v115, vcc
	v_rsq_f32_e32 v114, v114
	s_nop 0
	v_mul_f32_e32 v115, 0x45800000, v114
	v_cndmask_b32_e32 v114, v114, v115, vcc
	v_pk_mul_f32 v[106:107], v[106:107], v[114:115] op_sel_hi:[1,0]
	v_pk_mul_f32 v[104:105], v[104:105], v[114:115] op_sel_hi:[1,0]
	v_mul_f32_e32 v106, 0xbfb8aa3b, v106
	v_mul_f32_e32 v104, 0xbfb8aa3b, v104
	v_mul_f32_e32 v105, 0xbfb8aa3b, v105
	v_exp_f32_e32 v104, v104
	v_exp_f32_e32 v105, v105
	v_exp_f32_e32 v106, v106
	v_pk_mul_f32 v[110:111], v[110:111], v[114:115] op_sel_hi:[1,0]
	v_pk_mul_f32 v[108:109], v[108:109], v[114:115] op_sel_hi:[1,0]
	v_add_f32_e32 v104, 1.0, v104
	v_add_f32_e32 v105, 1.0, v105
	v_add_f32_e32 v106, 1.0, v106
	v_mul_f32_e32 v108, 0xbfb8aa3b, v108
	v_rcp_f32_e32 v115, v104
	v_mul_f32_e32 v104, 0xbfb8aa3b, v109
	v_rcp_f32_e32 v109, v105
	v_mul_f32_e32 v105, 0xbfb8aa3b, v110
	v_rcp_f32_e32 v110, v106
	v_mul_f32_e32 v106, 0xbfb8aa3b, v111
	v_mul_f32_e32 v107, 0xbfb8aa3b, v107
	v_exp_f32_e32 v108, v108
	v_exp_f32_e32 v104, v104
	v_exp_f32_e32 v105, v105
	v_exp_f32_e32 v106, v106
	v_exp_f32_e32 v107, v107
	v_pk_mul_f32 v[98:99], v[98:99], v[114:115] op_sel_hi:[1,0]
	v_pk_mul_f32 v[96:97], v[96:97], v[114:115] op_sel_hi:[1,0]
	v_add_f32_e32 v108, 1.0, v108
	v_add_f32_e32 v104, 1.0, v104
	v_add_f32_e32 v105, 1.0, v105
	v_add_f32_e32 v106, 1.0, v106
	v_add_f32_e32 v107, 1.0, v107
	v_mul_f32_e32 v96, 0xbfb8aa3b, v96
	v_mul_f32_e32 v97, 0xbfb8aa3b, v97
	v_mul_f32_e32 v98, 0xbfb8aa3b, v98
	v_rcp_f32_e32 v108, v108
	v_rcp_f32_e32 v104, v104
	v_rcp_f32_e32 v105, v105
	v_rcp_f32_e32 v106, v106
	v_rcp_f32_e32 v107, v107
	v_exp_f32_e32 v96, v96
	v_exp_f32_e32 v97, v97
	v_exp_f32_e32 v98, v98
	v_cvt_pk_bf16_f32 v104, v108, v104
	v_cvt_pk_bf16_f32 v105, v105, v106
	v_cvt_pk_bf16_f32 v106, v115, v109
	v_cvt_pk_bf16_f32 v107, v110, v107
	v_pk_mul_f32 v[102:103], v[102:103], v[114:115] op_sel_hi:[1,0]
	v_pk_mul_f32 v[100:101], v[100:101], v[114:115] op_sel_hi:[1,0]
	v_add_f32_e32 v96, 1.0, v96
	v_add_f32_e32 v97, 1.0, v97
	v_add_f32_e32 v98, 1.0, v98
	global_store_dwordx4 v[112:113], v[104:107], off
	v_mul_f32_e32 v100, 0xbfb8aa3b, v100
	v_mul_f32_e32 v99, 0xbfb8aa3b, v99
	v_rcp_f32_e32 v104, v96
	v_mul_f32_e32 v96, 0xbfb8aa3b, v101
	v_rcp_f32_e32 v101, v97
	v_mul_f32_e32 v97, 0xbfb8aa3b, v102
	v_rcp_f32_e32 v102, v98
	v_mul_f32_e32 v98, 0xbfb8aa3b, v103
	v_exp_f32_e32 v100, v100
	v_exp_f32_e32 v96, v96
	v_exp_f32_e32 v97, v97
	v_exp_f32_e32 v98, v98
	v_exp_f32_e32 v99, v99
	v_add_f32_e32 v100, 1.0, v100
	v_add_f32_e32 v96, 1.0, v96
	v_add_f32_e32 v97, 1.0, v97
	v_add_f32_e32 v98, 1.0, v98
	v_add_f32_e32 v99, 1.0, v99
	v_rcp_f32_e32 v100, v100
	v_rcp_f32_e32 v96, v96
	v_rcp_f32_e32 v97, v97
	v_rcp_f32_e32 v98, v98
	v_rcp_f32_e32 v99, v99
	v_cvt_pk_bf16_f32 v96, v100, v96
	v_cvt_pk_bf16_f32 v97, v97, v98
	v_cvt_pk_bf16_f32 v98, v104, v101
	v_cvt_pk_bf16_f32 v99, v102, v99
	global_store_dwordx4 v[112:113], v[96:99], off offset:256
	s_nop 1
	v_or_b32_e32 v98, 32, v142
	v_ashrrev_i32_e32 v99, 31, v98
	v_lshlrev_b64 v[96:97], 11, v[98:99]
	v_lshlrev_b64 v[98:99], 6, v[98:99]
	v_lshl_add_u64 v[96:97], v[144:145], 0, v[96:97]
	s_waitcnt vmcnt(9)
	v_mov_b32_e32 v102, v165
	v_mov_b32_e32 v103, v166
	v_mov_b32_e32 v99, v167
	v_mov_b32_e32 v98, v164
	v_pk_add_f32 v[98:99], v[102:103], v[98:99]
	s_nop 0
	v_add_f32_e32 v98, v98, v99
	v_mov_b32_e32 v99, v98
	s_nop 1
	v_permlane16_swap_b32_e32 v98, v99
	s_waitcnt lgkmcnt(0)
	v_add_f32_e32 v98, v98, v99
	v_mov_b32_e32 v99, v98
	s_nop 1
	v_permlane32_swap_b32_e32 v98, v99
	s_waitcnt lgkmcnt(0)
	v_add_f32_e32 v98, v98, v99
	v_fmamk_f32 v98, v98, 0x3a800000, v210
	v_cmp_gt_f32_e32 vcc, s39, v98
	v_mul_f32_e32 v99, 0x4b800000, v98
	s_nop 0
	v_cndmask_b32_e32 v98, v98, v99, vcc
	v_rsq_f32_e32 v98, v98
	s_nop 0
	v_mul_f32_e32 v99, 0x45800000, v98
	v_cndmask_b32_e32 v98, v98, v99, vcc
	v_pk_mul_f32 v[90:91], v[90:91], v[98:99] op_sel_hi:[1,0]
	v_pk_mul_f32 v[88:89], v[88:89], v[98:99] op_sel_hi:[1,0]
	v_mul_f32_e32 v90, 0xbfb8aa3b, v90
	v_mul_f32_e32 v88, 0xbfb8aa3b, v88
	v_mul_f32_e32 v89, 0xbfb8aa3b, v89
	v_exp_f32_e32 v88, v88
	v_exp_f32_e32 v89, v89
	v_exp_f32_e32 v90, v90
	v_pk_mul_f32 v[94:95], v[94:95], v[98:99] op_sel_hi:[1,0]
	v_pk_mul_f32 v[92:93], v[92:93], v[98:99] op_sel_hi:[1,0]
	v_add_f32_e32 v88, 1.0, v88
	v_add_f32_e32 v89, 1.0, v89
	v_add_f32_e32 v90, 1.0, v90
	v_mul_f32_e32 v92, 0xbfb8aa3b, v92
	v_rcp_f32_e32 v99, v88
	v_mul_f32_e32 v88, 0xbfb8aa3b, v93
	v_rcp_f32_e32 v93, v89
	v_mul_f32_e32 v89, 0xbfb8aa3b, v94
	v_rcp_f32_e32 v94, v90
	v_mul_f32_e32 v90, 0xbfb8aa3b, v95
	v_mul_f32_e32 v91, 0xbfb8aa3b, v91
	v_exp_f32_e32 v92, v92
	v_exp_f32_e32 v88, v88
	v_exp_f32_e32 v89, v89
	v_exp_f32_e32 v90, v90
	v_exp_f32_e32 v91, v91
	v_pk_mul_f32 v[82:83], v[82:83], v[98:99] op_sel_hi:[1,0]
	v_pk_mul_f32 v[80:81], v[80:81], v[98:99] op_sel_hi:[1,0]
	v_add_f32_e32 v92, 1.0, v92
	v_add_f32_e32 v88, 1.0, v88
	v_add_f32_e32 v89, 1.0, v89
	v_add_f32_e32 v90, 1.0, v90
	v_add_f32_e32 v91, 1.0, v91
	v_mul_f32_e32 v80, 0xbfb8aa3b, v80
	v_mul_f32_e32 v81, 0xbfb8aa3b, v81
	v_mul_f32_e32 v82, 0xbfb8aa3b, v82
	v_rcp_f32_e32 v92, v92
	v_rcp_f32_e32 v88, v88
	v_rcp_f32_e32 v89, v89
	v_rcp_f32_e32 v90, v90
	v_rcp_f32_e32 v91, v91
	v_exp_f32_e32 v80, v80
	v_exp_f32_e32 v81, v81
	v_exp_f32_e32 v82, v82
	v_cvt_pk_bf16_f32 v88, v92, v88
	v_cvt_pk_bf16_f32 v89, v89, v90
	v_cvt_pk_bf16_f32 v90, v99, v93
	v_cvt_pk_bf16_f32 v91, v94, v91
	v_pk_mul_f32 v[86:87], v[86:87], v[98:99] op_sel_hi:[1,0]
	v_pk_mul_f32 v[84:85], v[84:85], v[98:99] op_sel_hi:[1,0]
	v_add_f32_e32 v80, 1.0, v80
	v_add_f32_e32 v81, 1.0, v81
	v_add_f32_e32 v82, 1.0, v82
	global_store_dwordx4 v[96:97], v[88:91], off
	v_mul_f32_e32 v84, 0xbfb8aa3b, v84
	v_mul_f32_e32 v83, 0xbfb8aa3b, v83
	v_rcp_f32_e32 v88, v80
	v_mul_f32_e32 v80, 0xbfb8aa3b, v85
	v_rcp_f32_e32 v85, v81
	v_mul_f32_e32 v81, 0xbfb8aa3b, v86
	v_rcp_f32_e32 v86, v82
	v_mul_f32_e32 v82, 0xbfb8aa3b, v87
	v_exp_f32_e32 v84, v84
	v_exp_f32_e32 v80, v80
	v_exp_f32_e32 v81, v81
	v_exp_f32_e32 v82, v82
	v_exp_f32_e32 v83, v83
	v_add_f32_e32 v84, 1.0, v84
	v_add_f32_e32 v80, 1.0, v80
	v_add_f32_e32 v81, 1.0, v81
	v_add_f32_e32 v82, 1.0, v82
	v_add_f32_e32 v83, 1.0, v83
	v_rcp_f32_e32 v84, v84
	v_rcp_f32_e32 v80, v80
	v_rcp_f32_e32 v81, v81
	v_rcp_f32_e32 v82, v82
	v_rcp_f32_e32 v83, v83
	v_cvt_pk_bf16_f32 v80, v84, v80
	v_cvt_pk_bf16_f32 v81, v81, v82
	v_cvt_pk_bf16_f32 v82, v88, v85
	v_cvt_pk_bf16_f32 v83, v86, v83
	global_store_dwordx4 v[96:97], v[80:83], off offset:256
	s_nop 1
	v_or_b32_e32 v82, 48, v142
	v_ashrrev_i32_e32 v83, 31, v82
	v_lshlrev_b64 v[80:81], 11, v[82:83]
	v_lshlrev_b64 v[82:83], 6, v[82:83]
	v_lshl_add_u64 v[80:81], v[144:145], 0, v[80:81]
	s_waitcnt vmcnt(10)
; __device__ __forceinline__ float sigmoid_f(float x) { return __builtin_amdgcn_rcpf(1.0f + __builtin_amdgcn_exp2f(-1.4426950409f * x)); }
; __device__ __forceinline__ u32x4 pack8(const f32x4& v0, const f32x4& v1) { u32x4 w; w.x = cvt_pk_bf16(v0[0], v0[1]); w.y = cvt_pk_bf16(v0[2], v0[3]); w.z = cvt_pk_bf16(v1[0], v1[1]); w.w = cvt_pk_bf16(v1[2], v1[3]); return w; }
; __device__ __forceinline__ float row_rstd(const float* rss, long row, int fq) {
;     const f32x4 p = *(const f32x4*)(rss + row * 16 + fq * 4); float s = (p[0] + p[1]) + (p[2] + p[3]); s += __shfl_xor(s, 16); s += __shfl_xor(s, 32);
;     return rsqrtf(s * (1.0f / 1024.0f) + 1e-6f);
;     __device__ __forceinline__ void operator()(const f32x4 (&acc)[2][2][4][2], const Unit& u, int wr, int wc, int fr, int fq) const {
;     ...
;             for (int m = 0; m < 4; ++m) { bf16_t* rowp = base + (size_t)(row0 + ai * HALF + m * 16) * 1024 + col0; const float rn = row_rstd(rss, row0 + ai * HALF + m * 16, fq);
; #pragma unroll
;                 for (int bj = 0; bj < 2; ++bj) { f32x4 v0 = acc[ai][bj][m][0] * rn, v1 = acc[ai][bj][m][1] * rn;
; #pragma unroll
;                     for (int j = 0; j < 4; ++j) { v0[j] = sigmoid_f(v0[j]); v1[j] = sigmoid_f(v1[j]); }
;                     *(u32x4*)(rowp + bj * HALF) = pack8(v0, v1); } }
	v_mov_b32_e32 v86, v169
	v_mov_b32_e32 v87, v170
	v_mov_b32_e32 v83, v171
	v_mov_b32_e32 v82, v168
	v_pk_add_f32 v[82:83], v[86:87], v[82:83]
	s_nop 0
	v_add_f32_e32 v82, v82, v83
	v_mov_b32_e32 v83, v82
	s_nop 1
	v_permlane16_swap_b32_e32 v82, v83
	s_waitcnt lgkmcnt(0)
	v_add_f32_e32 v82, v82, v83
	v_mov_b32_e32 v83, v82
	s_nop 1
	v_permlane32_swap_b32_e32 v82, v83
	s_waitcnt lgkmcnt(0)
	v_add_f32_e32 v82, v82, v83
	v_fmamk_f32 v82, v82, 0x3a800000, v210
	v_cmp_gt_f32_e32 vcc, s39, v82
	v_mul_f32_e32 v83, 0x4b800000, v82
	s_nop 0
	v_cndmask_b32_e32 v82, v82, v83, vcc
	v_rsq_f32_e32 v82, v82
	s_nop 0
	v_mul_f32_e32 v83, 0x45800000, v82
	v_cndmask_b32_e32 v82, v82, v83, vcc
	v_pk_mul_f32 v[74:75], v[74:75], v[82:83] op_sel_hi:[1,0]
	v_pk_mul_f32 v[72:73], v[72:73], v[82:83] op_sel_hi:[1,0]
	v_mul_f32_e32 v74, 0xbfb8aa3b, v74
	v_mul_f32_e32 v72, 0xbfb8aa3b, v72
	v_mul_f32_e32 v73, 0xbfb8aa3b, v73
	v_exp_f32_e32 v72, v72
	v_exp_f32_e32 v73, v73
	v_exp_f32_e32 v74, v74
	v_pk_mul_f32 v[78:79], v[78:79], v[82:83] op_sel_hi:[1,0]
	v_pk_mul_f32 v[76:77], v[76:77], v[82:83] op_sel_hi:[1,0]
	v_add_f32_e32 v72, 1.0, v72
	v_add_f32_e32 v73, 1.0, v73
	v_add_f32_e32 v74, 1.0, v74
	v_mul_f32_e32 v76, 0xbfb8aa3b, v76
	v_rcp_f32_e32 v83, v72
	v_mul_f32_e32 v72, 0xbfb8aa3b, v77
	v_rcp_f32_e32 v77, v73
	v_mul_f32_e32 v73, 0xbfb8aa3b, v78
	v_rcp_f32_e32 v78, v74
	v_mul_f32_e32 v74, 0xbfb8aa3b, v79
	v_mul_f32_e32 v75, 0xbfb8aa3b, v75
	v_exp_f32_e32 v76, v76
	v_exp_f32_e32 v72, v72
	v_exp_f32_e32 v73, v73
	v_exp_f32_e32 v74, v74
	v_exp_f32_e32 v75, v75
	v_pk_mul_f32 v[66:67], v[66:67], v[82:83] op_sel_hi:[1,0]
	v_pk_mul_f32 v[64:65], v[64:65], v[82:83] op_sel_hi:[1,0]
	v_add_f32_e32 v76, 1.0, v76
	v_add_f32_e32 v72, 1.0, v72
	v_add_f32_e32 v73, 1.0, v73
	v_add_f32_e32 v74, 1.0, v74
	v_add_f32_e32 v75, 1.0, v75
	v_mul_f32_e32 v64, 0xbfb8aa3b, v64
	v_mul_f32_e32 v65, 0xbfb8aa3b, v65
	v_mul_f32_e32 v66, 0xbfb8aa3b, v66
	v_rcp_f32_e32 v76, v76
	v_rcp_f32_e32 v72, v72
	v_rcp_f32_e32 v73, v73
	v_rcp_f32_e32 v74, v74
	v_rcp_f32_e32 v75, v75
	v_exp_f32_e32 v64, v64
	v_exp_f32_e32 v65, v65
	v_exp_f32_e32 v66, v66
	v_cvt_pk_bf16_f32 v72, v76, v72
	v_cvt_pk_bf16_f32 v73, v73, v74
	v_cvt_pk_bf16_f32 v74, v83, v77
	v_cvt_pk_bf16_f32 v75, v78, v75
	v_pk_mul_f32 v[70:71], v[70:71], v[82:83] op_sel_hi:[1,0]
	v_pk_mul_f32 v[68:69], v[68:69], v[82:83] op_sel_hi:[1,0]
	v_add_f32_e32 v64, 1.0, v64
	v_add_f32_e32 v65, 1.0, v65
	v_add_f32_e32 v66, 1.0, v66
	global_store_dwordx4 v[80:81], v[72:75], off
	v_mul_f32_e32 v68, 0xbfb8aa3b, v68
	v_mul_f32_e32 v67, 0xbfb8aa3b, v67
	v_rcp_f32_e32 v72, v64
	v_mul_f32_e32 v64, 0xbfb8aa3b, v69
	v_rcp_f32_e32 v69, v65
	v_mul_f32_e32 v65, 0xbfb8aa3b, v70
	v_rcp_f32_e32 v70, v66
	v_mul_f32_e32 v66, 0xbfb8aa3b, v71
	v_exp_f32_e32 v68, v68
	v_exp_f32_e32 v64, v64
	v_exp_f32_e32 v65, v65
	v_exp_f32_e32 v66, v66
	v_exp_f32_e32 v67, v67
	v_add_f32_e32 v68, 1.0, v68
	v_add_f32_e32 v64, 1.0, v64
	v_add_f32_e32 v65, 1.0, v65
	v_add_f32_e32 v66, 1.0, v66
	v_add_f32_e32 v67, 1.0, v67
	v_rcp_f32_e32 v68, v68
	v_rcp_f32_e32 v64, v64
	v_rcp_f32_e32 v65, v65
	v_rcp_f32_e32 v66, v66
	v_rcp_f32_e32 v67, v67
	v_cvt_pk_bf16_f32 v64, v68, v64
	v_cvt_pk_bf16_f32 v65, v65, v66
	v_cvt_pk_bf16_f32 v66, v72, v69
	v_cvt_pk_bf16_f32 v67, v70, v67
	global_store_dwordx4 v[80:81], v[64:67], off offset:256
	s_nop 1
	v_add_u32_e32 v66, 0x80, v142
	v_ashrrev_i32_e32 v67, 31, v66
	v_lshlrev_b64 v[64:65], 11, v[66:67]
	v_lshlrev_b64 v[66:67], 6, v[66:67]
	v_lshl_add_u64 v[64:65], v[144:145], 0, v[64:65]
	s_waitcnt vmcnt(11)
	v_mov_b32_e32 v70, v173
	v_mov_b32_e32 v71, v174
	v_mov_b32_e32 v67, v175
	v_mov_b32_e32 v66, v172
	v_pk_add_f32 v[66:67], v[70:71], v[66:67]
	s_nop 0
	v_add_f32_e32 v66, v66, v67
	v_mov_b32_e32 v67, v66
	s_nop 1
	v_permlane16_swap_b32_e32 v66, v67
	s_waitcnt lgkmcnt(0)
	v_add_f32_e32 v66, v66, v67
	v_mov_b32_e32 v67, v66
	s_nop 1
	v_permlane32_swap_b32_e32 v66, v67
	s_waitcnt lgkmcnt(0)
	v_add_f32_e32 v66, v66, v67
	v_fmamk_f32 v66, v66, 0x3a800000, v210
	v_cmp_gt_f32_e32 vcc, s39, v66
	v_mul_f32_e32 v67, 0x4b800000, v66
	s_nop 0
	v_cndmask_b32_e32 v66, v66, v67, vcc
	v_rsq_f32_e32 v66, v66
	s_nop 0
	v_mul_f32_e32 v67, 0x45800000, v66
	v_cndmask_b32_e32 v66, v66, v67, vcc
	v_pk_mul_f32 v[58:59], v[58:59], v[66:67] op_sel_hi:[1,0]
	v_pk_mul_f32 v[56:57], v[56:57], v[66:67] op_sel_hi:[1,0]
	v_mul_f32_e32 v58, 0xbfb8aa3b, v58
	v_mul_f32_e32 v56, 0xbfb8aa3b, v56
	v_mul_f32_e32 v57, 0xbfb8aa3b, v57
	v_exp_f32_e32 v56, v56
	v_exp_f32_e32 v57, v57
	v_exp_f32_e32 v58, v58
	v_pk_mul_f32 v[62:63], v[62:63], v[66:67] op_sel_hi:[1,0]
	v_pk_mul_f32 v[60:61], v[60:61], v[66:67] op_sel_hi:[1,0]
	v_add_f32_e32 v56, 1.0, v56
	v_add_f32_e32 v57, 1.0, v57
	v_add_f32_e32 v58, 1.0, v58
	v_mul_f32_e32 v60, 0xbfb8aa3b, v60
	v_rcp_f32_e32 v67, v56
	v_mul_f32_e32 v56, 0xbfb8aa3b, v61
	v_rcp_f32_e32 v61, v57
	v_mul_f32_e32 v57, 0xbfb8aa3b, v62
	v_rcp_f32_e32 v62, v58
	v_mul_f32_e32 v58, 0xbfb8aa3b, v63
	v_mul_f32_e32 v59, 0xbfb8aa3b, v59
	v_exp_f32_e32 v60, v60
	v_exp_f32_e32 v56, v56
	v_exp_f32_e32 v57, v57
	v_exp_f32_e32 v58, v58
	v_exp_f32_e32 v59, v59
	v_pk_mul_f32 v[50:51], v[50:51], v[66:67] op_sel_hi:[1,0]
	v_pk_mul_f32 v[48:49], v[48:49], v[66:67] op_sel_hi:[1,0]
	v_add_f32_e32 v60, 1.0, v60
	v_add_f32_e32 v56, 1.0, v56
	v_add_f32_e32 v57, 1.0, v57
	v_add_f32_e32 v58, 1.0, v58
	v_add_f32_e32 v59, 1.0, v59
	v_mul_f32_e32 v48, 0xbfb8aa3b, v48
	v_mul_f32_e32 v49, 0xbfb8aa3b, v49
	v_mul_f32_e32 v50, 0xbfb8aa3b, v50
	v_rcp_f32_e32 v60, v60
	v_rcp_f32_e32 v56, v56
	v_rcp_f32_e32 v57, v57
	v_rcp_f32_e32 v58, v58
	v_rcp_f32_e32 v59, v59
	v_exp_f32_e32 v48, v48
	v_exp_f32_e32 v49, v49
; __device__ __forceinline__ float sigmoid_f(float x) { return __builtin_amdgcn_rcpf(1.0f + __builtin_amdgcn_exp2f(-1.4426950409f * x)); }
; __device__ __forceinline__ u32x4 pack8(const f32x4& v0, const f32x4& v1) { u32x4 w; w.x = cvt_pk_bf16(v0[0], v0[1]); w.y = cvt_pk_bf16(v0[2], v0[3]); w.z = cvt_pk_bf16(v1[0], v1[1]); w.w = cvt_pk_bf16(v1[2], v1[3]); return w; }
; __device__ __forceinline__ float row_rstd(const float* rss, long row, int fq) {
;     const f32x4 p = *(const f32x4*)(rss + row * 16 + fq * 4); float s = (p[0] + p[1]) + (p[2] + p[3]); s += __shfl_xor(s, 16); s += __shfl_xor(s, 32);
;     return rsqrtf(s * (1.0f / 1024.0f) + 1e-6f);
;     __device__ __forceinline__ void operator()(const f32x4 (&acc)[2][2][4][2], const Unit& u, int wr, int wc, int fr, int fq) const {
;     ...
;             for (int m = 0; m < 4; ++m) { bf16_t* rowp = base + (size_t)(row0 + ai * HALF + m * 16) * 1024 + col0; const float rn = row_rstd(rss, row0 + ai * HALF + m * 16, fq);
; #pragma unroll
;                 for (int bj = 0; bj < 2; ++bj) { f32x4 v0 = acc[ai][bj][m][0] * rn, v1 = acc[ai][bj][m][1] * rn;
; #pragma unroll
;                     for (int j = 0; j < 4; ++j) { v0[j] = sigmoid_f(v0[j]); v1[j] = sigmoid_f(v1[j]); }
;                     *(u32x4*)(rowp + bj * HALF) = pack8(v0, v1); } }
	v_exp_f32_e32 v50, v50
	v_cvt_pk_bf16_f32 v56, v60, v56
	v_cvt_pk_bf16_f32 v57, v57, v58
	v_cvt_pk_bf16_f32 v58, v67, v61
	v_cvt_pk_bf16_f32 v59, v62, v59
	v_pk_mul_f32 v[54:55], v[54:55], v[66:67] op_sel_hi:[1,0]
	v_pk_mul_f32 v[52:53], v[52:53], v[66:67] op_sel_hi:[1,0]
	v_add_f32_e32 v48, 1.0, v48
	v_add_f32_e32 v49, 1.0, v49
	v_add_f32_e32 v50, 1.0, v50
	global_store_dwordx4 v[64:65], v[56:59], off
	v_mul_f32_e32 v52, 0xbfb8aa3b, v52
	v_mul_f32_e32 v51, 0xbfb8aa3b, v51
	v_rcp_f32_e32 v56, v48
	v_mul_f32_e32 v48, 0xbfb8aa3b, v53
	v_rcp_f32_e32 v53, v49
	v_mul_f32_e32 v49, 0xbfb8aa3b, v54
	v_rcp_f32_e32 v54, v50
	v_mul_f32_e32 v50, 0xbfb8aa3b, v55
	v_exp_f32_e32 v52, v52
	v_exp_f32_e32 v48, v48
	v_exp_f32_e32 v49, v49
	v_exp_f32_e32 v50, v50
	v_exp_f32_e32 v51, v51
	v_add_f32_e32 v52, 1.0, v52
	v_add_f32_e32 v48, 1.0, v48
	v_add_f32_e32 v49, 1.0, v49
	v_add_f32_e32 v50, 1.0, v50
	v_add_f32_e32 v51, 1.0, v51
	v_rcp_f32_e32 v52, v52
	v_rcp_f32_e32 v48, v48
	v_rcp_f32_e32 v49, v49
	v_rcp_f32_e32 v50, v50
	v_rcp_f32_e32 v51, v51
	v_cvt_pk_bf16_f32 v48, v52, v48
	v_cvt_pk_bf16_f32 v49, v49, v50
	v_cvt_pk_bf16_f32 v50, v56, v53
	v_cvt_pk_bf16_f32 v51, v54, v51
	global_store_dwordx4 v[64:65], v[48:51], off offset:256
	s_nop 1
	v_add_u32_e32 v50, 0x90, v142
	v_ashrrev_i32_e32 v51, 31, v50
	v_lshlrev_b64 v[48:49], 11, v[50:51]
	v_lshlrev_b64 v[50:51], 6, v[50:51]
	v_lshl_add_u64 v[48:49], v[144:145], 0, v[48:49]
	s_waitcnt vmcnt(12)
	v_mov_b32_e32 v54, v177
	v_mov_b32_e32 v55, v178
	v_mov_b32_e32 v51, v179
	v_mov_b32_e32 v50, v176
	v_pk_add_f32 v[50:51], v[54:55], v[50:51]
	s_nop 0
	v_add_f32_e32 v50, v50, v51
	v_mov_b32_e32 v51, v50
	s_nop 1
	v_permlane16_swap_b32_e32 v50, v51
	s_waitcnt lgkmcnt(0)
	v_add_f32_e32 v50, v50, v51
	v_mov_b32_e32 v51, v50
	s_nop 1
	v_permlane32_swap_b32_e32 v50, v51
	s_waitcnt lgkmcnt(0)
	v_add_f32_e32 v50, v50, v51
	v_fmamk_f32 v50, v50, 0x3a800000, v210
	v_cmp_gt_f32_e32 vcc, s39, v50
	v_mul_f32_e32 v51, 0x4b800000, v50
	s_nop 0
	v_cndmask_b32_e32 v50, v50, v51, vcc
	v_rsq_f32_e32 v50, v50
	s_nop 0
	v_mul_f32_e32 v51, 0x45800000, v50
	v_cndmask_b32_e32 v50, v50, v51, vcc
	v_pk_mul_f32 v[42:43], v[42:43], v[50:51] op_sel_hi:[1,0]
	v_pk_mul_f32 v[40:41], v[40:41], v[50:51] op_sel_hi:[1,0]
	v_mul_f32_e32 v42, 0xbfb8aa3b, v42
	v_mul_f32_e32 v40, 0xbfb8aa3b, v40
	v_mul_f32_e32 v41, 0xbfb8aa3b, v41
	v_exp_f32_e32 v40, v40
	v_exp_f32_e32 v41, v41
	v_exp_f32_e32 v42, v42
	v_pk_mul_f32 v[46:47], v[46:47], v[50:51] op_sel_hi:[1,0]
	v_pk_mul_f32 v[44:45], v[44:45], v[50:51] op_sel_hi:[1,0]
	v_add_f32_e32 v40, 1.0, v40
	v_add_f32_e32 v41, 1.0, v41
	v_add_f32_e32 v42, 1.0, v42
	v_mul_f32_e32 v44, 0xbfb8aa3b, v44
	v_rcp_f32_e32 v51, v40
	v_mul_f32_e32 v40, 0xbfb8aa3b, v45
	v_rcp_f32_e32 v45, v41
	v_mul_f32_e32 v41, 0xbfb8aa3b, v46
	v_rcp_f32_e32 v46, v42
	v_mul_f32_e32 v42, 0xbfb8aa3b, v47
	v_mul_f32_e32 v43, 0xbfb8aa3b, v43
	v_exp_f32_e32 v44, v44
	v_exp_f32_e32 v40, v40
	v_exp_f32_e32 v41, v41
	v_exp_f32_e32 v42, v42
	v_exp_f32_e32 v43, v43
	v_pk_mul_f32 v[34:35], v[34:35], v[50:51] op_sel_hi:[1,0]
	v_pk_mul_f32 v[32:33], v[32:33], v[50:51] op_sel_hi:[1,0]
	v_add_f32_e32 v44, 1.0, v44
	v_add_f32_e32 v40, 1.0, v40
	v_add_f32_e32 v41, 1.0, v41
	v_add_f32_e32 v42, 1.0, v42
	v_add_f32_e32 v43, 1.0, v43
	v_mul_f32_e32 v32, 0xbfb8aa3b, v32
	v_mul_f32_e32 v33, 0xbfb8aa3b, v33
	v_mul_f32_e32 v34, 0xbfb8aa3b, v34
	v_rcp_f32_e32 v44, v44
	v_rcp_f32_e32 v40, v40
	v_rcp_f32_e32 v41, v41
	v_rcp_f32_e32 v42, v42
	v_rcp_f32_e32 v43, v43
	v_exp_f32_e32 v32, v32
	v_exp_f32_e32 v33, v33
	v_exp_f32_e32 v34, v34
	v_cvt_pk_bf16_f32 v40, v44, v40
	v_cvt_pk_bf16_f32 v41, v41, v42
	v_cvt_pk_bf16_f32 v42, v51, v45
	v_cvt_pk_bf16_f32 v43, v46, v43
	v_pk_mul_f32 v[38:39], v[38:39], v[50:51] op_sel_hi:[1,0]
	v_pk_mul_f32 v[36:37], v[36:37], v[50:51] op_sel_hi:[1,0]
	v_add_f32_e32 v32, 1.0, v32
	v_add_f32_e32 v33, 1.0, v33
	v_add_f32_e32 v34, 1.0, v34
	global_store_dwordx4 v[48:49], v[40:43], off
	v_mul_f32_e32 v36, 0xbfb8aa3b, v36
	v_mul_f32_e32 v35, 0xbfb8aa3b, v35
	v_rcp_f32_e32 v40, v32
	v_mul_f32_e32 v32, 0xbfb8aa3b, v37
	v_rcp_f32_e32 v37, v33
	v_mul_f32_e32 v33, 0xbfb8aa3b, v38
	v_rcp_f32_e32 v38, v34
	v_mul_f32_e32 v34, 0xbfb8aa3b, v39
	v_exp_f32_e32 v36, v36
	v_exp_f32_e32 v32, v32
	v_exp_f32_e32 v33, v33
	v_exp_f32_e32 v34, v34
	v_exp_f32_e32 v35, v35
	v_add_f32_e32 v36, 1.0, v36
	v_add_f32_e32 v32, 1.0, v32
	v_add_f32_e32 v33, 1.0, v33
	v_add_f32_e32 v34, 1.0, v34
	v_add_f32_e32 v35, 1.0, v35
	v_rcp_f32_e32 v36, v36
	v_rcp_f32_e32 v32, v32
	v_rcp_f32_e32 v33, v33
	v_rcp_f32_e32 v34, v34
	v_rcp_f32_e32 v35, v35
	v_cvt_pk_bf16_f32 v32, v36, v32
	v_cvt_pk_bf16_f32 v33, v33, v34
	v_cvt_pk_bf16_f32 v34, v40, v37
	v_cvt_pk_bf16_f32 v35, v38, v35
	global_store_dwordx4 v[48:49], v[32:35], off offset:256
	s_nop 1
	v_add_u32_e32 v34, 0xa0, v142
	v_ashrrev_i32_e32 v35, 31, v34
	v_lshlrev_b64 v[32:33], 11, v[34:35]
	v_lshlrev_b64 v[34:35], 6, v[34:35]
	v_lshl_add_u64 v[32:33], v[144:145], 0, v[32:33]
	s_waitcnt vmcnt(13)
	v_mov_b32_e32 v38, v181
	v_mov_b32_e32 v39, v182
	v_mov_b32_e32 v35, v183
	v_mov_b32_e32 v34, v180
	v_pk_add_f32 v[34:35], v[38:39], v[34:35]
	s_nop 0
	v_add_f32_e32 v34, v34, v35
	v_mov_b32_e32 v35, v34
	s_nop 1
	v_permlane16_swap_b32_e32 v34, v35
	s_waitcnt lgkmcnt(0)
	v_add_f32_e32 v34, v34, v35
	v_mov_b32_e32 v35, v34
	s_nop 1
	v_permlane32_swap_b32_e32 v34, v35
	s_waitcnt lgkmcnt(0)
; __device__ __forceinline__ float sigmoid_f(float x) { return __builtin_amdgcn_rcpf(1.0f + __builtin_amdgcn_exp2f(-1.4426950409f * x)); }
; __device__ __forceinline__ u32x4 pack8(const f32x4& v0, const f32x4& v1) { u32x4 w; w.x = cvt_pk_bf16(v0[0], v0[1]); w.y = cvt_pk_bf16(v0[2], v0[3]); w.z = cvt_pk_bf16(v1[0], v1[1]); w.w = cvt_pk_bf16(v1[2], v1[3]); return w; }
; __device__ __forceinline__ float row_rstd(const float* rss, long row, int fq) {
;     const f32x4 p = *(const f32x4*)(rss + row * 16 + fq * 4); float s = (p[0] + p[1]) + (p[2] + p[3]); s += __shfl_xor(s, 16); s += __shfl_xor(s, 32);
;     return rsqrtf(s * (1.0f / 1024.0f) + 1e-6f);
;     __device__ __forceinline__ void operator()(const f32x4 (&acc)[2][2][4][2], const Unit& u, int wr, int wc, int fr, int fq) const {
;     ...
;             for (int m = 0; m < 4; ++m) { bf16_t* rowp = base + (size_t)(row0 + ai * HALF + m * 16) * 1024 + col0; const float rn = row_rstd(rss, row0 + ai * HALF + m * 16, fq);
; #pragma unroll
;                 for (int bj = 0; bj < 2; ++bj) { f32x4 v0 = acc[ai][bj][m][0] * rn, v1 = acc[ai][bj][m][1] * rn;
; #pragma unroll
;                     for (int j = 0; j < 4; ++j) { v0[j] = sigmoid_f(v0[j]); v1[j] = sigmoid_f(v1[j]); }
;                     *(u32x4*)(rowp + bj * HALF) = pack8(v0, v1); } }
	v_add_f32_e32 v34, v34, v35
	v_fmamk_f32 v34, v34, 0x3a800000, v210
	v_cmp_gt_f32_e32 vcc, s39, v34
	v_mul_f32_e32 v35, 0x4b800000, v34
	s_nop 0
	v_cndmask_b32_e32 v34, v34, v35, vcc
	v_rsq_f32_e32 v34, v34
	s_nop 0
	v_mul_f32_e32 v35, 0x45800000, v34
	v_cndmask_b32_e32 v34, v34, v35, vcc
	v_pk_mul_f32 v[26:27], v[26:27], v[34:35] op_sel_hi:[1,0]
	v_pk_mul_f32 v[24:25], v[24:25], v[34:35] op_sel_hi:[1,0]
	v_mul_f32_e32 v26, 0xbfb8aa3b, v26
	v_mul_f32_e32 v24, 0xbfb8aa3b, v24
	v_mul_f32_e32 v25, 0xbfb8aa3b, v25
	v_exp_f32_e32 v24, v24
	v_exp_f32_e32 v25, v25
	v_exp_f32_e32 v26, v26
	v_pk_mul_f32 v[30:31], v[30:31], v[34:35] op_sel_hi:[1,0]
	v_pk_mul_f32 v[28:29], v[28:29], v[34:35] op_sel_hi:[1,0]
	v_add_f32_e32 v24, 1.0, v24
	v_add_f32_e32 v25, 1.0, v25
	v_add_f32_e32 v26, 1.0, v26
	v_mul_f32_e32 v28, 0xbfb8aa3b, v28
	v_rcp_f32_e32 v35, v24
	v_mul_f32_e32 v24, 0xbfb8aa3b, v29
	v_rcp_f32_e32 v29, v25
	v_mul_f32_e32 v25, 0xbfb8aa3b, v30
	v_rcp_f32_e32 v30, v26
	v_mul_f32_e32 v26, 0xbfb8aa3b, v31
	v_mul_f32_e32 v27, 0xbfb8aa3b, v27
	v_exp_f32_e32 v28, v28
	v_exp_f32_e32 v24, v24
	v_exp_f32_e32 v25, v25
	v_exp_f32_e32 v26, v26
	v_exp_f32_e32 v27, v27
	v_pk_mul_f32 v[18:19], v[18:19], v[34:35] op_sel_hi:[1,0]
	v_pk_mul_f32 v[16:17], v[16:17], v[34:35] op_sel_hi:[1,0]
	v_add_f32_e32 v28, 1.0, v28
	v_add_f32_e32 v24, 1.0, v24
	v_add_f32_e32 v25, 1.0, v25
	v_add_f32_e32 v26, 1.0, v26
	v_add_f32_e32 v27, 1.0, v27
	v_mul_f32_e32 v16, 0xbfb8aa3b, v16
	v_mul_f32_e32 v17, 0xbfb8aa3b, v17
	v_mul_f32_e32 v18, 0xbfb8aa3b, v18
	v_rcp_f32_e32 v28, v28
	v_rcp_f32_e32 v24, v24
	v_rcp_f32_e32 v25, v25
	v_rcp_f32_e32 v26, v26
	v_rcp_f32_e32 v27, v27
	v_exp_f32_e32 v16, v16
	v_exp_f32_e32 v17, v17
	v_exp_f32_e32 v18, v18
	v_cvt_pk_bf16_f32 v24, v28, v24
	v_cvt_pk_bf16_f32 v25, v25, v26
	v_cvt_pk_bf16_f32 v26, v35, v29
	v_cvt_pk_bf16_f32 v27, v30, v27
	v_pk_mul_f32 v[22:23], v[22:23], v[34:35] op_sel_hi:[1,0]
	v_pk_mul_f32 v[20:21], v[20:21], v[34:35] op_sel_hi:[1,0]
	v_add_f32_e32 v16, 1.0, v16
	v_add_f32_e32 v17, 1.0, v17
	v_add_f32_e32 v18, 1.0, v18
	global_store_dwordx4 v[32:33], v[24:27], off
	v_mul_f32_e32 v20, 0xbfb8aa3b, v20
	v_mul_f32_e32 v19, 0xbfb8aa3b, v19
	v_rcp_f32_e32 v24, v16
	v_mul_f32_e32 v16, 0xbfb8aa3b, v21
	v_rcp_f32_e32 v21, v17
	v_mul_f32_e32 v17, 0xbfb8aa3b, v22
	v_rcp_f32_e32 v22, v18
	v_mul_f32_e32 v18, 0xbfb8aa3b, v23
	v_exp_f32_e32 v20, v20
	v_exp_f32_e32 v16, v16
	v_exp_f32_e32 v17, v17
	v_exp_f32_e32 v18, v18
	v_exp_f32_e32 v19, v19
	v_add_f32_e32 v20, 1.0, v20
	v_add_f32_e32 v16, 1.0, v16
	v_add_f32_e32 v17, 1.0, v17
	v_add_f32_e32 v18, 1.0, v18
	v_add_f32_e32 v19, 1.0, v19
	v_rcp_f32_e32 v20, v20
	v_rcp_f32_e32 v16, v16
	v_rcp_f32_e32 v17, v17
	v_rcp_f32_e32 v18, v18
	v_rcp_f32_e32 v19, v19
	v_cvt_pk_bf16_f32 v16, v20, v16
	v_cvt_pk_bf16_f32 v17, v17, v18
	v_cvt_pk_bf16_f32 v18, v24, v21
	v_cvt_pk_bf16_f32 v19, v22, v19
	global_store_dwordx4 v[32:33], v[16:19], off offset:256
	s_nop 1
	v_add_u32_e32 v18, 0xb0, v142
	v_ashrrev_i32_e32 v19, 31, v18
	v_lshlrev_b64 v[16:17], 11, v[18:19]
	v_lshlrev_b64 v[18:19], 6, v[18:19]
	v_lshl_add_u64 v[16:17], v[144:145], 0, v[16:17]
	s_waitcnt vmcnt(14)
	v_mov_b32_e32 v22, v185
	v_mov_b32_e32 v23, v186
	v_mov_b32_e32 v19, v187
	v_mov_b32_e32 v18, v184
	v_pk_add_f32 v[18:19], v[22:23], v[18:19]
	s_nop 0
	v_add_f32_e32 v18, v18, v19
	v_mov_b32_e32 v19, v18
	s_nop 1
	v_permlane16_swap_b32_e32 v18, v19
	s_waitcnt lgkmcnt(0)
	v_add_f32_e32 v18, v18, v19
	v_mov_b32_e32 v19, v18
	s_nop 1
	v_permlane32_swap_b32_e32 v18, v19
	s_waitcnt lgkmcnt(0)
	v_add_f32_e32 v18, v18, v19
	v_fmamk_f32 v18, v18, 0x3a800000, v210
	v_cmp_gt_f32_e32 vcc, s39, v18
	v_mul_f32_e32 v19, 0x4b800000, v18
	s_nop 0
	v_cndmask_b32_e32 v18, v18, v19, vcc
	v_rsq_f32_e32 v18, v18
	s_nop 0
	v_mul_f32_e32 v19, 0x45800000, v18
	v_cndmask_b32_e32 v18, v18, v19, vcc
	v_pk_mul_f32 v[10:11], v[10:11], v[18:19] op_sel_hi:[1,0]
	v_pk_mul_f32 v[8:9], v[8:9], v[18:19] op_sel_hi:[1,0]
	v_mul_f32_e32 v10, 0xbfb8aa3b, v10
	v_mul_f32_e32 v8, 0xbfb8aa3b, v8
	v_mul_f32_e32 v9, 0xbfb8aa3b, v9
	v_exp_f32_e32 v8, v8
	v_exp_f32_e32 v9, v9
	v_exp_f32_e32 v10, v10
	v_pk_mul_f32 v[14:15], v[14:15], v[18:19] op_sel_hi:[1,0]
	v_pk_mul_f32 v[12:13], v[12:13], v[18:19] op_sel_hi:[1,0]
	v_add_f32_e32 v8, 1.0, v8
	v_add_f32_e32 v9, 1.0, v9
	v_add_f32_e32 v10, 1.0, v10
	v_mul_f32_e32 v12, 0xbfb8aa3b, v12
	v_rcp_f32_e32 v19, v8
	v_mul_f32_e32 v8, 0xbfb8aa3b, v13
	v_rcp_f32_e32 v13, v9
	v_mul_f32_e32 v9, 0xbfb8aa3b, v14
	v_rcp_f32_e32 v14, v10
	v_mul_f32_e32 v10, 0xbfb8aa3b, v15
	v_mul_f32_e32 v11, 0xbfb8aa3b, v11
	v_exp_f32_e32 v12, v12
	v_exp_f32_e32 v8, v8
	v_exp_f32_e32 v9, v9
	v_exp_f32_e32 v10, v10
	v_exp_f32_e32 v11, v11
	v_pk_mul_f32 v[2:3], v[2:3], v[18:19] op_sel_hi:[1,0]
	v_pk_mul_f32 v[0:1], v[0:1], v[18:19] op_sel_hi:[1,0]
	v_add_f32_e32 v12, 1.0, v12
	v_add_f32_e32 v8, 1.0, v8
	v_add_f32_e32 v9, 1.0, v9
	v_add_f32_e32 v10, 1.0, v10
	v_add_f32_e32 v11, 1.0, v11
	v_mul_f32_e32 v0, 0xbfb8aa3b, v0
	v_mul_f32_e32 v1, 0xbfb8aa3b, v1
	v_mul_f32_e32 v2, 0xbfb8aa3b, v2
	v_rcp_f32_e32 v12, v12
	v_rcp_f32_e32 v8, v8
	v_rcp_f32_e32 v9, v9
	v_rcp_f32_e32 v10, v10
	v_rcp_f32_e32 v11, v11
	v_exp_f32_e32 v0, v0
	v_exp_f32_e32 v1, v1
	v_exp_f32_e32 v2, v2
	v_cvt_pk_bf16_f32 v8, v12, v8
	v_cvt_pk_bf16_f32 v9, v9, v10
	v_cvt_pk_bf16_f32 v10, v19, v13
	v_cvt_pk_bf16_f32 v11, v14, v11
	v_pk_mul_f32 v[6:7], v[6:7], v[18:19] op_sel_hi:[1,0]
	v_pk_mul_f32 v[4:5], v[4:5], v[18:19] op_sel_hi:[1,0]
	v_add_f32_e32 v0, 1.0, v0
	v_add_f32_e32 v1, 1.0, v1
	v_add_f32_e32 v2, 1.0, v2
	global_store_dwordx4 v[16:17], v[8:11], off
	v_mul_f32_e32 v4, 0xbfb8aa3b, v4
	v_mul_f32_e32 v3, 0xbfb8aa3b, v3
	v_rcp_f32_e32 v8, v0
	v_mul_f32_e32 v0, 0xbfb8aa3b, v5
	v_rcp_f32_e32 v5, v1
	v_mul_f32_e32 v1, 0xbfb8aa3b, v6
	v_rcp_f32_e32 v6, v2
	v_mul_f32_e32 v2, 0xbfb8aa3b, v7
	v_exp_f32_e32 v4, v4
	v_exp_f32_e32 v0, v0
	v_exp_f32_e32 v1, v1
	v_exp_f32_e32 v2, v2
	v_exp_f32_e32 v3, v3
	v_add_f32_e32 v4, 1.0, v4
	v_add_f32_e32 v0, 1.0, v0
	v_add_f32_e32 v1, 1.0, v1
	v_add_f32_e32 v2, 1.0, v2
	v_add_f32_e32 v3, 1.0, v3
	v_rcp_f32_e32 v4, v4
	v_rcp_f32_e32 v0, v0
	v_rcp_f32_e32 v1, v1
	v_rcp_f32_e32 v2, v2
	v_rcp_f32_e32 v3, v3
	v_cvt_pk_bf16_f32 v0, v4, v0
	s_andn2_b64 vcc, exec, s[40:41]
	v_cvt_pk_bf16_f32 v1, v1, v2
	v_cvt_pk_bf16_f32 v2, v8, v5
	v_cvt_pk_bf16_f32 v3, v6, v3
	global_store_dwordx4 v[16:17], v[0:3], off offset:256
	s_cbranch_vccnz .LBB0_182
	s_andn2_b64 vcc, exec, s[4:5]
	s_cbranch_vccnz .LBB0_181
	s_barrier
	s_branch .LBB0_181

; __device__ __forceinline__ float row_rstd(const float* rss, long row, int fq) {
;     const f32x4 p = *(const f32x4*)(rss + row * 16 + fq * 4); float s = (p[0] + p[1]) + (p[2] + p[3]); s += __shfl_xor(s, 16); s += __shfl_xor(s, 32);
;     return rsqrtf(s * (1.0f / 1024.0f) + 1e-6f);
;     __device__ __forceinline__ void operator()(const f32x4 (&acc)[2][2][4][2], const Unit& u, int wr, int wc, int fr, int fq) const {
;         const int t = u.pn >> 2, row0 = u.pm * BM + wr * 64 + fr, col0 = (u.pn & 3) * BM + wc * 32 + 8 * fq;
;         bf16_t* base = (t == 4) ? O4 : O0 + (size_t)t * stride;
;         const float sc = (t == 2) ? qscale : 1.f;
; #pragma unroll
;         for (int ai = 0; ai < 2; ++ai)
; #pragma unroll
;             for (int m = 0; m < 4; ++m) { const int row = row0 + ai * HALF + m * 16; bf16_t* rowp = base + (size_t)row * 1024 + col0; float ss = 0.f; const float rn = row_rstd(rss, row, fq);
; #pragma unroll
;                 for (int bj = 0; bj < 2; ++bj) { f32x4 v0 = acc[ai][bj][m][0] * rn, v1 = acc[ai][bj][m][1] * rn;
;                     if (t <= 1) {
; #pragma unroll
;                         for (int j = 0; j < 4; ++j) { v0[j] = gelu_t(v0[j]); v1[j] = gelu_t(v1[j]); }
; #pragma unroll
;                         for (int j = 0; j < 4; ++j) ss += v0[j] * v0[j] + v1[j] * v1[j];
.LBB0_337:
	v_lshl_add_u32 v142, s4, 8, v154
	v_ashrrev_i32_e32 v143, 31, v142
	v_lshlrev_b64 v[144:145], 6, v[142:143]
	v_lshl_add_u64 v[146:147], v[136:137], 0, v[144:145]
	v_mov_b32_e32 v194, v146
	v_mov_b32_e32 v195, v147
	v_add_co_u32_e32 v192, vcc, 0x2000, v146
	s_nop 1
	v_addc_co_u32_e32 v193, vcc, 0, v147, vcc
	global_load_dwordx4 v[146:149], v[146:147], off
	global_load_dwordx4 v[164:167], v[194:195], off offset:1024
	global_load_dwordx4 v[168:171], v[194:195], off offset:2048
	global_load_dwordx4 v[172:175], v[194:195], off offset:3072
	global_load_dwordx4 v[176:179], v[192:193], off
	global_load_dwordx4 v[180:183], v[192:193], off offset:1024
	global_load_dwordx4 v[184:187], v[192:193], off offset:2048
	global_load_dwordx4 v[188:191], v[192:193], off offset:3072
	v_cmp_lt_i32_e32 vcc, v251, v246
	s_ashr_i32 s6, s10, 2
	s_cmp_lt_i32 s6, 2
	v_cndmask_b32_e32 v150, v245, v251, vcc
	v_lshlrev_b32_e32 v158, 2, v150
	v_cmp_lt_i32_e32 vcc, v252, v246
	s_cselect_b64 s[8:9], -1, 0
	s_cmp_gt_i32 s6, 1
	v_mov_b32_e32 v160, 0
	s_waitcnt vmcnt(7)
	v_mov_b32_e32 v150, v147
	v_mov_b32_e32 v151, v148
	v_mov_b32_e32 v147, v149
	v_pk_add_f32 v[146:147], v[150:151], v[146:147]
	v_cndmask_b32_e32 v148, v245, v252, vcc
	v_add_f32_e32 v146, v146, v147
	v_mov_b32_e32 v147, v146
	s_nop 1
	v_permlane16_swap_b32_e32 v146, v147
	v_lshlrev_b32_e32 v159, 2, v148
	s_waitcnt lgkmcnt(0)
	v_add_f32_e32 v146, v146, v147
	v_mov_b32_e32 v147, v146
	s_nop 1
	v_permlane32_swap_b32_e32 v146, v147
	s_waitcnt lgkmcnt(0)
	v_add_f32_e32 v146, v146, v147
	v_fmamk_f32 v146, v146, 0x3a800000, v210
	v_mul_f32_e32 v147, 0x4b800000, v146
	v_cmp_gt_f32_e32 vcc, s39, v146
	s_nop 1
	v_cndmask_b32_e32 v146, v146, v147, vcc
	v_rsq_f32_e32 v146, v146
	s_nop 0
	v_mul_f32_e32 v147, 0x45800000, v146
	v_cndmask_b32_e32 v146, v146, v147, vcc
	v_pk_mul_f32 v[148:149], v[126:127], v[146:147] op_sel_hi:[1,0]
	v_pk_mul_f32 v[126:127], v[124:125], v[146:147] op_sel_hi:[1,0]
	v_pk_mul_f32 v[152:153], v[122:123], v[146:147] op_sel_hi:[1,0]
	v_pk_mul_f32 v[150:151], v[120:121], v[146:147] op_sel_hi:[1,0]
	s_cbranch_scc1 .LBB0_339
	v_mul_f32_e32 v122, 0x3d122279, v127
	v_fmaak_f32 v122, v127, v122, 0x3f4c422a
	v_mul_f32_e32 v122, v127, v122
	v_mul_f32_e32 v121, 0x3d122279, v150
	v_mul_f32_e32 v122, 0xc038aa3b, v122
	v_fmaak_f32 v121, v150, v121, 0x3f4c422a
	v_exp_f32_e32 v123, v122
	v_mul_f32_e32 v122, 0x3d122279, v151
	v_mul_f32_e32 v121, v150, v121
	v_fmaak_f32 v122, v151, v122, 0x3f4c422a
	v_mul_f32_e32 v121, 0xc038aa3b, v121
	v_mul_f32_e32 v122, v151, v122
	v_exp_f32_e32 v121, v121
	v_mul_f32_e32 v122, 0xc038aa3b, v122
	v_exp_f32_e32 v124, v122
	v_mul_f32_e32 v125, 0x3d122279, v152
	v_mul_f32_e32 v120, 0x3d122279, v126
	v_add_f32_e32 v121, 1.0, v121
	v_fmaak_f32 v125, v152, v125, 0x3f4c422a
	v_mul_f32_e32 v147, 0x3d122279, v149
	v_mul_f32_e32 v160, 0x3d122279, v153
	v_fmaak_f32 v120, v126, v120, 0x3f4c422a
	v_rcp_f32_e32 v122, v121
	v_add_f32_e32 v121, 1.0, v123
	v_add_f32_e32 v123, 1.0, v124
	v_mul_f32_e32 v124, 0x3d122279, v148
	v_mul_f32_e32 v125, v152, v125
	v_fmaak_f32 v147, v149, v147, 0x3f4c422a
	v_fmaak_f32 v160, v153, v160, 0x3f4c422a
	v_mul_f32_e32 v120, v126, v120
	v_fmaak_f32 v124, v148, v124, 0x3f4c422a
	v_mul_f32_e32 v125, 0xc038aa3b, v125
	v_mul_f32_e32 v147, v149, v147
	v_mul_f32_e32 v160, v153, v160
	v_mul_f32_e32 v120, 0xc038aa3b, v120
	v_mul_f32_e32 v124, v148, v124
	v_exp_f32_e32 v125, v125
	v_mul_f32_e32 v147, 0xc038aa3b, v147
	v_mul_f32_e32 v160, 0xc038aa3b, v160
	v_exp_f32_e32 v120, v120
	v_mul_f32_e32 v124, 0xc038aa3b, v124
	v_exp_f32_e32 v147, v147
	v_exp_f32_e32 v161, v160
	v_exp_f32_e32 v124, v124
	v_add_f32_e32 v125, 1.0, v125
	v_add_f32_e32 v120, 1.0, v120
	v_rcp_f32_e32 v123, v123
	v_rcp_f32_e32 v160, v125
	v_add_f32_e32 v125, 1.0, v147
	v_add_f32_e32 v147, 1.0, v161
	v_rcp_f32_e32 v120, v120
	v_rcp_f32_e32 v121, v121
	v_add_f32_e32 v124, 1.0, v124
	v_rcp_f32_e32 v161, v147
	v_rcp_f32_e32 v124, v124
	v_rcp_f32_e32 v125, v125
	v_pk_mul_f32 v[150:151], v[150:151], v[122:123]
	v_pk_mul_f32 v[126:127], v[126:127], v[120:121]
	v_pk_mul_f32 v[120:121], v[150:151], v[150:151]
	v_pk_mul_f32 v[152:153], v[152:153], v[160:161]
	v_pk_fma_f32 v[120:121], v[126:127], v[126:127], v[120:121]
	v_pk_mul_f32 v[148:149], v[148:149], v[124:125]
	v_pk_mul_f32 v[122:123], v[152:153], v[152:153]
	v_add_f32_e32 v120, v120, v121
	v_pk_fma_f32 v[122:123], v[148:149], v[148:149], v[122:123]
	s_nop 0
	v_add_f32_e32 v120, v122, v120
	v_add_f32_e32 v160, v123, v120

; __device__ __forceinline__ float row_rstd(const float* rss, long row, int fq) {
;     const f32x4 p = *(const f32x4*)(rss + row * 16 + fq * 4); float s = (p[0] + p[1]) + (p[2] + p[3]); s += __shfl_xor(s, 16); s += __shfl_xor(s, 32);
;     return rsqrtf(s * (1.0f / 1024.0f) + 1e-6f);
;     __device__ __forceinline__ void operator()(const f32x4 (&acc)[2][2][4][2], const Unit& u, int wr, int wc, int fr, int fq) const {
;     ...
;             for (int m = 0; m < 4; ++m) { const int row = row0 + ai * HALF + m * 16; bf16_t* rowp = base + (size_t)row * 1024 + col0; float ss = 0.f; const float rn = row_rstd(rss, row, fq);
; #pragma unroll
;                 for (int bj = 0; bj < 2; ++bj) { f32x4 v0 = acc[ai][bj][m][0] * rn, v1 = acc[ai][bj][m][1] * rn;
;                     if (t <= 1) {
; #pragma unroll
;                         for (int j = 0; j < 4; ++j) { v0[j] = gelu_t(v0[j]); v1[j] = gelu_t(v1[j]); }
; #pragma unroll
;                         for (int j = 0; j < 4; ++j) ss += v0[j] * v0[j] + v1[j] * v1[j];
.LBB0_345:
	s_nop 0
	v_or_b32_e32 v114, 16, v142
	v_ashrrev_i32_e32 v115, 31, v114
	s_waitcnt lgkmcnt(0)
	v_lshlrev_b64 v[112:113], 6, v[114:115]
	s_and_b64 vcc, exec, s[4:5]
	v_mov_b32_e32 v126, 0
	s_waitcnt vmcnt(8)
	v_mov_b32_e32 v124, v165
	v_mov_b32_e32 v125, v166
	v_mov_b32_e32 v117, v167
	v_mov_b32_e32 v116, v164
	v_pk_add_f32 v[116:117], v[124:125], v[116:117]
	s_nop 0
	v_add_f32_e32 v116, v116, v117
	v_mov_b32_e32 v117, v116
	s_nop 1
	v_permlane16_swap_b32_e32 v116, v117
	s_waitcnt lgkmcnt(0)
	v_add_f32_e32 v116, v116, v117
	v_mov_b32_e32 v117, v116
	s_nop 1
	v_permlane32_swap_b32_e32 v116, v117
	s_waitcnt lgkmcnt(0)
	v_add_f32_e32 v116, v116, v117
	v_fmamk_f32 v116, v116, 0x3a800000, v210
	v_mul_f32_e32 v117, 0x4b800000, v116
	v_cmp_gt_f32_e64 s[6:7], s39, v116
	s_nop 1
	v_cndmask_b32_e64 v116, v116, v117, s[6:7]
	v_rsq_f32_e32 v116, v116
	s_nop 0
	v_mul_f32_e32 v117, 0x45800000, v116
	v_cndmask_b32_e64 v116, v116, v117, s[6:7]
	v_pk_mul_f32 v[124:125], v[110:111], v[116:117] op_sel_hi:[1,0]
	v_pk_mul_f32 v[118:119], v[108:109], v[116:117] op_sel_hi:[1,0]
	v_pk_mul_f32 v[110:111], v[106:107], v[116:117] op_sel_hi:[1,0]
	v_pk_mul_f32 v[108:109], v[104:105], v[116:117] op_sel_hi:[1,0]
	s_cbranch_vccnz .LBB0_347
	v_mul_f32_e32 v106, 0x3d122279, v119
	v_fmaak_f32 v106, v119, v106, 0x3f4c422a
	v_mul_f32_e32 v106, v119, v106
	v_mul_f32_e32 v105, 0x3d122279, v108
	v_mul_f32_e32 v106, 0xc038aa3b, v106
	v_fmaak_f32 v105, v108, v105, 0x3f4c422a
	v_exp_f32_e32 v107, v106
	v_mul_f32_e32 v106, 0x3d122279, v109
	v_mul_f32_e32 v105, v108, v105
	v_fmaak_f32 v106, v109, v106, 0x3f4c422a
	v_mul_f32_e32 v105, 0xc038aa3b, v105
	v_mul_f32_e32 v106, v109, v106
	v_exp_f32_e32 v105, v105
	v_mul_f32_e32 v106, 0xc038aa3b, v106
	v_exp_f32_e32 v117, v106
	v_mul_f32_e32 v126, 0x3d122279, v110
	v_add_f32_e32 v105, 1.0, v105
	v_rcp_f32_e32 v106, v105
	v_add_f32_e32 v105, 1.0, v107
	v_add_f32_e32 v107, 1.0, v117
	v_mul_f32_e32 v117, 0x3d122279, v124
	v_fmaak_f32 v117, v124, v117, 0x3f4c422a
	v_mul_f32_e32 v117, v124, v117
	v_fmaak_f32 v126, v110, v126, 0x3f4c422a
	v_mul_f32_e32 v117, 0xc038aa3b, v117
	v_mul_f32_e32 v126, v110, v126
	v_exp_f32_e32 v117, v117
	v_mul_f32_e32 v126, 0xc038aa3b, v126
	v_exp_f32_e32 v127, v126
	v_mul_f32_e32 v104, 0x3d122279, v118
	v_add_f32_e32 v117, 1.0, v117
	v_rcp_f32_e32 v126, v117
	v_add_f32_e32 v117, 1.0, v127
	v_mul_f32_e32 v127, 0x3d122279, v125
	v_fmaak_f32 v127, v125, v127, 0x3f4c422a
	v_mul_f32_e32 v143, 0x3d122279, v111
	v_fmaak_f32 v104, v118, v104, 0x3f4c422a
	v_mul_f32_e32 v127, v125, v127
	v_fmaak_f32 v143, v111, v143, 0x3f4c422a
	v_mul_f32_e32 v104, v118, v104
	v_mul_f32_e32 v127, 0xc038aa3b, v127
	v_mul_f32_e32 v143, v111, v143
	v_mul_f32_e32 v104, 0xc038aa3b, v104
	v_exp_f32_e32 v127, v127
	v_mul_f32_e32 v143, 0xc038aa3b, v143
	v_exp_f32_e32 v104, v104
	v_exp_f32_e32 v143, v143
	v_rcp_f32_e32 v144, v117
	v_add_f32_e32 v117, 1.0, v127
	v_add_f32_e32 v104, 1.0, v104
	v_rcp_f32_e32 v107, v107
	v_rcp_f32_e32 v127, v117
	v_add_f32_e32 v117, 1.0, v143
	v_rcp_f32_e32 v104, v104
	v_rcp_f32_e32 v105, v105
	v_rcp_f32_e32 v145, v117
	v_pk_mul_f32 v[108:109], v[108:109], v[106:107]
	v_pk_mul_f32 v[124:125], v[124:125], v[126:127]
	v_pk_mul_f32 v[118:119], v[118:119], v[104:105]
	v_pk_mul_f32 v[104:105], v[108:109], v[108:109]
	v_pk_mul_f32 v[110:111], v[110:111], v[144:145]
	v_pk_fma_f32 v[104:105], v[118:119], v[118:119], v[104:105]
	v_pk_mul_f32 v[106:107], v[110:111], v[110:111]
	v_add_f32_e32 v104, v104, v105
	v_pk_fma_f32 v[106:107], v[124:125], v[124:125], v[106:107]
	s_nop 0
	v_add_f32_e32 v104, v106, v104
	v_add_f32_e32 v126, v107, v104

; __device__ __forceinline__ float row_rstd(const float* rss, long row, int fq) {
;     const f32x4 p = *(const f32x4*)(rss + row * 16 + fq * 4); float s = (p[0] + p[1]) + (p[2] + p[3]); s += __shfl_xor(s, 16); s += __shfl_xor(s, 32);
;     return rsqrtf(s * (1.0f / 1024.0f) + 1e-6f);
;     __device__ __forceinline__ void operator()(const f32x4 (&acc)[2][2][4][2], const Unit& u, int wr, int wc, int fr, int fq) const {
;     ...
;             for (int m = 0; m < 4; ++m) { const int row = row0 + ai * HALF + m * 16; bf16_t* rowp = base + (size_t)row * 1024 + col0; float ss = 0.f; const float rn = row_rstd(rss, row, fq);
; #pragma unroll
;                 for (int bj = 0; bj < 2; ++bj) { f32x4 v0 = acc[ai][bj][m][0] * rn, v1 = acc[ai][bj][m][1] * rn;
;                     if (t <= 1) {
; #pragma unroll
;                         for (int j = 0; j < 4; ++j) { v0[j] = gelu_t(v0[j]); v1[j] = gelu_t(v1[j]); }
; #pragma unroll
;                         for (int j = 0; j < 4; ++j) ss += v0[j] * v0[j] + v1[j] * v1[j];
.LBB0_353:
	s_nop 0
	v_or_b32_e32 v98, 32, v142
	v_ashrrev_i32_e32 v99, 31, v98
	s_waitcnt lgkmcnt(0)
	v_lshlrev_b64 v[96:97], 6, v[98:99]
	s_and_b64 vcc, exec, s[4:5]
	v_mov_b32_e32 v106, 0
	s_waitcnt vmcnt(9)
	v_mov_b32_e32 v104, v169
	v_mov_b32_e32 v105, v170
	v_mov_b32_e32 v101, v171
	v_mov_b32_e32 v100, v168
	v_pk_add_f32 v[100:101], v[104:105], v[100:101]
	s_nop 0
	v_add_f32_e32 v100, v100, v101
	v_mov_b32_e32 v101, v100
	s_nop 1
	v_permlane16_swap_b32_e32 v100, v101
	s_waitcnt lgkmcnt(0)
	v_add_f32_e32 v100, v100, v101
	v_mov_b32_e32 v101, v100
	s_nop 1
	v_permlane32_swap_b32_e32 v100, v101
	s_waitcnt lgkmcnt(0)
	v_add_f32_e32 v100, v100, v101
	v_fmamk_f32 v100, v100, 0x3a800000, v210
	v_mul_f32_e32 v101, 0x4b800000, v100
	v_cmp_gt_f32_e64 s[8:9], s39, v100
	s_nop 1
	v_cndmask_b32_e64 v100, v100, v101, s[8:9]
	v_rsq_f32_e32 v100, v100
	s_nop 0
	v_mul_f32_e32 v101, 0x45800000, v100
	v_cndmask_b32_e64 v100, v100, v101, s[8:9]
	v_pk_mul_f32 v[104:105], v[94:95], v[100:101] op_sel_hi:[1,0]
	v_pk_mul_f32 v[102:103], v[92:93], v[100:101] op_sel_hi:[1,0]
	v_pk_mul_f32 v[94:95], v[90:91], v[100:101] op_sel_hi:[1,0]
	v_pk_mul_f32 v[92:93], v[88:89], v[100:101] op_sel_hi:[1,0]
	s_cbranch_vccnz .LBB0_355
	v_mul_f32_e32 v90, 0x3d122279, v103
	v_fmaak_f32 v90, v103, v90, 0x3f4c422a
	v_mul_f32_e32 v90, v103, v90
	v_mul_f32_e32 v89, 0x3d122279, v92
	v_mul_f32_e32 v90, 0xc038aa3b, v90
	v_fmaak_f32 v89, v92, v89, 0x3f4c422a
	v_exp_f32_e32 v91, v90
	v_mul_f32_e32 v90, 0x3d122279, v93
	v_mul_f32_e32 v89, v92, v89
	v_fmaak_f32 v90, v93, v90, 0x3f4c422a
	v_mul_f32_e32 v89, 0xc038aa3b, v89
	v_mul_f32_e32 v90, v93, v90
	v_exp_f32_e32 v89, v89
	v_mul_f32_e32 v90, 0xc038aa3b, v90
	v_exp_f32_e32 v101, v90
	v_mul_f32_e32 v106, 0x3d122279, v94
	v_add_f32_e32 v89, 1.0, v89
	v_rcp_f32_e32 v90, v89
	v_add_f32_e32 v89, 1.0, v91
	v_add_f32_e32 v91, 1.0, v101
	v_mul_f32_e32 v101, 0x3d122279, v104
	v_fmaak_f32 v101, v104, v101, 0x3f4c422a
	v_mul_f32_e32 v101, v104, v101
	v_fmaak_f32 v106, v94, v106, 0x3f4c422a
	v_mul_f32_e32 v101, 0xc038aa3b, v101
	v_mul_f32_e32 v106, v94, v106
	v_exp_f32_e32 v101, v101
	v_mul_f32_e32 v106, 0xc038aa3b, v106
	v_exp_f32_e32 v107, v106
	v_mul_f32_e32 v88, 0x3d122279, v102
	v_add_f32_e32 v101, 1.0, v101
	v_rcp_f32_e32 v106, v101
	v_add_f32_e32 v101, 1.0, v107
	v_mul_f32_e32 v107, 0x3d122279, v105
	v_fmaak_f32 v107, v105, v107, 0x3f4c422a
	v_mul_f32_e32 v108, 0x3d122279, v95
	v_fmaak_f32 v88, v102, v88, 0x3f4c422a
	v_mul_f32_e32 v107, v105, v107
	v_fmaak_f32 v108, v95, v108, 0x3f4c422a
	v_mul_f32_e32 v88, v102, v88
	v_mul_f32_e32 v107, 0xc038aa3b, v107
	v_mul_f32_e32 v108, v95, v108
	v_mul_f32_e32 v88, 0xc038aa3b, v88
	v_exp_f32_e32 v107, v107
	v_mul_f32_e32 v108, 0xc038aa3b, v108
	v_exp_f32_e32 v88, v88
	v_exp_f32_e32 v109, v108
	v_rcp_f32_e32 v108, v101
	v_add_f32_e32 v101, 1.0, v107
	v_add_f32_e32 v88, 1.0, v88
	v_rcp_f32_e32 v91, v91
	v_rcp_f32_e32 v107, v101
	v_add_f32_e32 v101, 1.0, v109
	v_rcp_f32_e32 v88, v88
	v_rcp_f32_e32 v89, v89
	v_rcp_f32_e32 v109, v101
	v_pk_mul_f32 v[92:93], v[92:93], v[90:91]
	v_pk_mul_f32 v[104:105], v[104:105], v[106:107]
	v_pk_mul_f32 v[102:103], v[102:103], v[88:89]
	v_pk_mul_f32 v[88:89], v[92:93], v[92:93]
	v_pk_mul_f32 v[94:95], v[94:95], v[108:109]
	v_pk_fma_f32 v[88:89], v[102:103], v[102:103], v[88:89]
	v_pk_mul_f32 v[90:91], v[94:95], v[94:95]
	v_add_f32_e32 v88, v88, v89
	v_pk_fma_f32 v[90:91], v[104:105], v[104:105], v[90:91]
	s_nop 0
	v_add_f32_e32 v88, v90, v88
	v_add_f32_e32 v106, v91, v88

; __device__ __forceinline__ float row_rstd(const float* rss, long row, int fq) {
;     const f32x4 p = *(const f32x4*)(rss + row * 16 + fq * 4); float s = (p[0] + p[1]) + (p[2] + p[3]); s += __shfl_xor(s, 16); s += __shfl_xor(s, 32);
;     return rsqrtf(s * (1.0f / 1024.0f) + 1e-6f);
;     __device__ __forceinline__ void operator()(const f32x4 (&acc)[2][2][4][2], const Unit& u, int wr, int wc, int fr, int fq) const {
;     ...
;             for (int m = 0; m < 4; ++m) { const int row = row0 + ai * HALF + m * 16; bf16_t* rowp = base + (size_t)row * 1024 + col0; float ss = 0.f; const float rn = row_rstd(rss, row, fq);
; #pragma unroll
;                 for (int bj = 0; bj < 2; ++bj) { f32x4 v0 = acc[ai][bj][m][0] * rn, v1 = acc[ai][bj][m][1] * rn;
;                     if (t <= 1) {
; #pragma unroll
;                         for (int j = 0; j < 4; ++j) { v0[j] = gelu_t(v0[j]); v1[j] = gelu_t(v1[j]); }
; #pragma unroll
;                         for (int j = 0; j < 4; ++j) ss += v0[j] * v0[j] + v1[j] * v1[j];
.LBB0_361:
	s_nop 0
	v_or_b32_e32 v82, 48, v142
	v_ashrrev_i32_e32 v83, 31, v82
	s_waitcnt lgkmcnt(0)
	v_lshlrev_b64 v[80:81], 6, v[82:83]
	s_and_b64 vcc, exec, s[4:5]
	v_mov_b32_e32 v90, 0
	s_waitcnt vmcnt(10)
	v_mov_b32_e32 v88, v173
	v_mov_b32_e32 v89, v174
	v_mov_b32_e32 v85, v175
	v_mov_b32_e32 v84, v172
	v_pk_add_f32 v[84:85], v[88:89], v[84:85]
	s_nop 0
	v_add_f32_e32 v84, v84, v85
	v_mov_b32_e32 v85, v84
	s_nop 1
	v_permlane16_swap_b32_e32 v84, v85
	s_waitcnt lgkmcnt(0)
	v_add_f32_e32 v84, v84, v85
	v_mov_b32_e32 v85, v84
	s_nop 1
	v_permlane32_swap_b32_e32 v84, v85
	s_waitcnt lgkmcnt(0)
	v_add_f32_e32 v84, v84, v85
	v_fmamk_f32 v84, v84, 0x3a800000, v210
	v_mul_f32_e32 v85, 0x4b800000, v84
	v_cmp_gt_f32_e64 s[8:9], s39, v84
	s_nop 1
	v_cndmask_b32_e64 v84, v84, v85, s[8:9]
	v_rsq_f32_e32 v84, v84
	s_nop 0
	v_mul_f32_e32 v85, 0x45800000, v84
	v_cndmask_b32_e64 v84, v84, v85, s[8:9]
	v_pk_mul_f32 v[88:89], v[78:79], v[84:85] op_sel_hi:[1,0]
	v_pk_mul_f32 v[86:87], v[76:77], v[84:85] op_sel_hi:[1,0]
	v_pk_mul_f32 v[78:79], v[74:75], v[84:85] op_sel_hi:[1,0]
	v_pk_mul_f32 v[76:77], v[72:73], v[84:85] op_sel_hi:[1,0]
	s_cbranch_vccnz .LBB0_363
	v_mul_f32_e32 v74, 0x3d122279, v87
	v_fmaak_f32 v74, v87, v74, 0x3f4c422a
	v_mul_f32_e32 v74, v87, v74
	v_mul_f32_e32 v73, 0x3d122279, v76
	v_mul_f32_e32 v74, 0xc038aa3b, v74
	v_fmaak_f32 v73, v76, v73, 0x3f4c422a
	v_exp_f32_e32 v75, v74
	v_mul_f32_e32 v74, 0x3d122279, v77
	v_mul_f32_e32 v73, v76, v73
	v_fmaak_f32 v74, v77, v74, 0x3f4c422a
	v_mul_f32_e32 v73, 0xc038aa3b, v73
	v_mul_f32_e32 v74, v77, v74
	v_exp_f32_e32 v73, v73
	v_mul_f32_e32 v74, 0xc038aa3b, v74
	v_exp_f32_e32 v85, v74
	v_mul_f32_e32 v90, 0x3d122279, v78
	v_add_f32_e32 v73, 1.0, v73
	v_rcp_f32_e32 v74, v73
	v_add_f32_e32 v73, 1.0, v75
	v_add_f32_e32 v75, 1.0, v85
	v_mul_f32_e32 v85, 0x3d122279, v88
	v_fmaak_f32 v85, v88, v85, 0x3f4c422a
	v_mul_f32_e32 v85, v88, v85
	v_fmaak_f32 v90, v78, v90, 0x3f4c422a
	v_mul_f32_e32 v85, 0xc038aa3b, v85
	v_mul_f32_e32 v90, v78, v90
	v_exp_f32_e32 v85, v85
	v_mul_f32_e32 v90, 0xc038aa3b, v90
	v_exp_f32_e32 v91, v90
	v_mul_f32_e32 v72, 0x3d122279, v86
	v_add_f32_e32 v85, 1.0, v85
	v_rcp_f32_e32 v90, v85
	v_add_f32_e32 v85, 1.0, v91
	v_mul_f32_e32 v91, 0x3d122279, v89
	v_fmaak_f32 v91, v89, v91, 0x3f4c422a
	v_mul_f32_e32 v92, 0x3d122279, v79
	v_fmaak_f32 v72, v86, v72, 0x3f4c422a
	v_mul_f32_e32 v91, v89, v91
	v_fmaak_f32 v92, v79, v92, 0x3f4c422a
	v_mul_f32_e32 v72, v86, v72
	v_mul_f32_e32 v91, 0xc038aa3b, v91
	v_mul_f32_e32 v92, v79, v92
	v_mul_f32_e32 v72, 0xc038aa3b, v72
	v_exp_f32_e32 v91, v91
	v_mul_f32_e32 v92, 0xc038aa3b, v92
	v_exp_f32_e32 v72, v72
	v_exp_f32_e32 v93, v92
	v_rcp_f32_e32 v92, v85
	v_add_f32_e32 v85, 1.0, v91
	v_add_f32_e32 v72, 1.0, v72
	v_rcp_f32_e32 v75, v75
	v_rcp_f32_e32 v91, v85
	v_add_f32_e32 v85, 1.0, v93
	v_rcp_f32_e32 v72, v72
	v_rcp_f32_e32 v73, v73
	v_rcp_f32_e32 v93, v85
	v_pk_mul_f32 v[76:77], v[76:77], v[74:75]
	v_pk_mul_f32 v[88:89], v[88:89], v[90:91]
	v_pk_mul_f32 v[86:87], v[86:87], v[72:73]
	v_pk_mul_f32 v[72:73], v[76:77], v[76:77]
	v_pk_mul_f32 v[78:79], v[78:79], v[92:93]
	v_pk_fma_f32 v[72:73], v[86:87], v[86:87], v[72:73]
	v_pk_mul_f32 v[74:75], v[78:79], v[78:79]
	v_add_f32_e32 v72, v72, v73
	v_pk_fma_f32 v[74:75], v[88:89], v[88:89], v[74:75]
	s_nop 0
	v_add_f32_e32 v72, v74, v72
	v_add_f32_e32 v90, v75, v72

; __device__ __forceinline__ float row_rstd(const float* rss, long row, int fq) {
;     const f32x4 p = *(const f32x4*)(rss + row * 16 + fq * 4); float s = (p[0] + p[1]) + (p[2] + p[3]); s += __shfl_xor(s, 16); s += __shfl_xor(s, 32);
;     return rsqrtf(s * (1.0f / 1024.0f) + 1e-6f);
;     __device__ __forceinline__ void operator()(const f32x4 (&acc)[2][2][4][2], const Unit& u, int wr, int wc, int fr, int fq) const {
;     ...
;             for (int m = 0; m < 4; ++m) { const int row = row0 + ai * HALF + m * 16; bf16_t* rowp = base + (size_t)row * 1024 + col0; float ss = 0.f; const float rn = row_rstd(rss, row, fq);
; #pragma unroll
;                 for (int bj = 0; bj < 2; ++bj) { f32x4 v0 = acc[ai][bj][m][0] * rn, v1 = acc[ai][bj][m][1] * rn;
;                     if (t <= 1) {
; #pragma unroll
;                         for (int j = 0; j < 4; ++j) { v0[j] = gelu_t(v0[j]); v1[j] = gelu_t(v1[j]); }
; #pragma unroll
;                         for (int j = 0; j < 4; ++j) ss += v0[j] * v0[j] + v1[j] * v1[j];
.LBB0_369:
	s_nop 0
	v_add_u32_e32 v66, 0x80, v142
	v_ashrrev_i32_e32 v67, 31, v66
	s_waitcnt lgkmcnt(0)
	v_lshlrev_b64 v[64:65], 6, v[66:67]
	s_and_b64 vcc, exec, s[4:5]
	v_mov_b32_e32 v74, 0
	s_waitcnt vmcnt(11)
	v_mov_b32_e32 v72, v177
	v_mov_b32_e32 v73, v178
	v_mov_b32_e32 v69, v179
	v_mov_b32_e32 v68, v176
	v_pk_add_f32 v[68:69], v[72:73], v[68:69]
	s_nop 0
	v_add_f32_e32 v68, v68, v69
	v_mov_b32_e32 v69, v68
	s_nop 1
	v_permlane16_swap_b32_e32 v68, v69
	s_waitcnt lgkmcnt(0)
	v_add_f32_e32 v68, v68, v69
	v_mov_b32_e32 v69, v68
	s_nop 1
	v_permlane32_swap_b32_e32 v68, v69
	s_waitcnt lgkmcnt(0)
	v_add_f32_e32 v68, v68, v69
	v_fmamk_f32 v68, v68, 0x3a800000, v210
	v_mul_f32_e32 v69, 0x4b800000, v68
	v_cmp_gt_f32_e64 s[8:9], s39, v68
	s_nop 1
	v_cndmask_b32_e64 v68, v68, v69, s[8:9]
	v_rsq_f32_e32 v68, v68
	s_nop 0
	v_mul_f32_e32 v69, 0x45800000, v68
	v_cndmask_b32_e64 v68, v68, v69, s[8:9]
	v_pk_mul_f32 v[72:73], v[62:63], v[68:69] op_sel_hi:[1,0]
	v_pk_mul_f32 v[70:71], v[60:61], v[68:69] op_sel_hi:[1,0]
	v_pk_mul_f32 v[62:63], v[58:59], v[68:69] op_sel_hi:[1,0]
	v_pk_mul_f32 v[60:61], v[56:57], v[68:69] op_sel_hi:[1,0]
	s_cbranch_vccnz .LBB0_371
	v_mul_f32_e32 v58, 0x3d122279, v71
	v_fmaak_f32 v58, v71, v58, 0x3f4c422a
	v_mul_f32_e32 v58, v71, v58
	v_mul_f32_e32 v57, 0x3d122279, v60
	v_mul_f32_e32 v58, 0xc038aa3b, v58
	v_fmaak_f32 v57, v60, v57, 0x3f4c422a
	v_exp_f32_e32 v59, v58
	v_mul_f32_e32 v58, 0x3d122279, v61
	v_mul_f32_e32 v57, v60, v57
	v_fmaak_f32 v58, v61, v58, 0x3f4c422a
	v_mul_f32_e32 v57, 0xc038aa3b, v57
	v_mul_f32_e32 v58, v61, v58
	v_exp_f32_e32 v57, v57
	v_mul_f32_e32 v58, 0xc038aa3b, v58
	v_exp_f32_e32 v69, v58
	v_mul_f32_e32 v74, 0x3d122279, v62
	v_add_f32_e32 v57, 1.0, v57
	v_rcp_f32_e32 v58, v57
	v_add_f32_e32 v57, 1.0, v59
	v_add_f32_e32 v59, 1.0, v69
	v_mul_f32_e32 v69, 0x3d122279, v72
	v_fmaak_f32 v69, v72, v69, 0x3f4c422a
	v_mul_f32_e32 v69, v72, v69
	v_fmaak_f32 v74, v62, v74, 0x3f4c422a
	v_mul_f32_e32 v69, 0xc038aa3b, v69
	v_mul_f32_e32 v74, v62, v74
	v_exp_f32_e32 v69, v69
	v_mul_f32_e32 v74, 0xc038aa3b, v74
	v_exp_f32_e32 v75, v74
	v_mul_f32_e32 v56, 0x3d122279, v70
	v_add_f32_e32 v69, 1.0, v69
	v_rcp_f32_e32 v74, v69
	v_add_f32_e32 v69, 1.0, v75
	v_mul_f32_e32 v75, 0x3d122279, v73
	v_fmaak_f32 v75, v73, v75, 0x3f4c422a
	v_mul_f32_e32 v76, 0x3d122279, v63
	v_fmaak_f32 v56, v70, v56, 0x3f4c422a
	v_mul_f32_e32 v75, v73, v75
	v_fmaak_f32 v76, v63, v76, 0x3f4c422a
	v_mul_f32_e32 v56, v70, v56
	v_mul_f32_e32 v75, 0xc038aa3b, v75
	v_mul_f32_e32 v76, v63, v76
	v_mul_f32_e32 v56, 0xc038aa3b, v56
	v_exp_f32_e32 v75, v75
	v_mul_f32_e32 v76, 0xc038aa3b, v76
	v_exp_f32_e32 v56, v56
	v_exp_f32_e32 v77, v76
	v_rcp_f32_e32 v76, v69
	v_add_f32_e32 v69, 1.0, v75
	v_add_f32_e32 v56, 1.0, v56
	v_rcp_f32_e32 v59, v59
	v_rcp_f32_e32 v75, v69
	v_add_f32_e32 v69, 1.0, v77
	v_rcp_f32_e32 v56, v56
	v_rcp_f32_e32 v57, v57
	v_rcp_f32_e32 v77, v69
	v_pk_mul_f32 v[60:61], v[60:61], v[58:59]
	v_pk_mul_f32 v[72:73], v[72:73], v[74:75]
	v_pk_mul_f32 v[70:71], v[70:71], v[56:57]
	v_pk_mul_f32 v[56:57], v[60:61], v[60:61]
	v_pk_mul_f32 v[62:63], v[62:63], v[76:77]
	v_pk_fma_f32 v[56:57], v[70:71], v[70:71], v[56:57]
	v_pk_mul_f32 v[58:59], v[62:63], v[62:63]
	v_add_f32_e32 v56, v56, v57
	v_pk_fma_f32 v[58:59], v[72:73], v[72:73], v[58:59]
	s_nop 0
	v_add_f32_e32 v56, v58, v56
	v_add_f32_e32 v74, v59, v56

; __device__ __forceinline__ float row_rstd(const float* rss, long row, int fq) {
;     const f32x4 p = *(const f32x4*)(rss + row * 16 + fq * 4); float s = (p[0] + p[1]) + (p[2] + p[3]); s += __shfl_xor(s, 16); s += __shfl_xor(s, 32);
;     return rsqrtf(s * (1.0f / 1024.0f) + 1e-6f);
;     __device__ __forceinline__ void operator()(const f32x4 (&acc)[2][2][4][2], const Unit& u, int wr, int wc, int fr, int fq) const {
;     ...
;             for (int m = 0; m < 4; ++m) { const int row = row0 + ai * HALF + m * 16; bf16_t* rowp = base + (size_t)row * 1024 + col0; float ss = 0.f; const float rn = row_rstd(rss, row, fq);
; #pragma unroll
;                 for (int bj = 0; bj < 2; ++bj) { f32x4 v0 = acc[ai][bj][m][0] * rn, v1 = acc[ai][bj][m][1] * rn;
;                     if (t <= 1) {
; #pragma unroll
;                         for (int j = 0; j < 4; ++j) { v0[j] = gelu_t(v0[j]); v1[j] = gelu_t(v1[j]); }
; #pragma unroll
;                         for (int j = 0; j < 4; ++j) ss += v0[j] * v0[j] + v1[j] * v1[j];
.LBB0_377:
	s_nop 0
	v_add_u32_e32 v50, 0x90, v142
	v_ashrrev_i32_e32 v51, 31, v50
	s_waitcnt lgkmcnt(0)
	v_lshlrev_b64 v[48:49], 6, v[50:51]
	s_and_b64 vcc, exec, s[4:5]
	v_mov_b32_e32 v58, 0
	s_waitcnt vmcnt(12)
	v_mov_b32_e32 v56, v181
	v_mov_b32_e32 v57, v182
	v_mov_b32_e32 v53, v183
	v_mov_b32_e32 v52, v180
	v_pk_add_f32 v[52:53], v[56:57], v[52:53]
	s_nop 0
	v_add_f32_e32 v52, v52, v53
	v_mov_b32_e32 v53, v52
	s_nop 1
	v_permlane16_swap_b32_e32 v52, v53
	s_waitcnt lgkmcnt(0)
	v_add_f32_e32 v52, v52, v53
	v_mov_b32_e32 v53, v52
	s_nop 1
	v_permlane32_swap_b32_e32 v52, v53
	s_waitcnt lgkmcnt(0)
	v_add_f32_e32 v52, v52, v53
	v_fmamk_f32 v52, v52, 0x3a800000, v210
	v_mul_f32_e32 v53, 0x4b800000, v52
	v_cmp_gt_f32_e64 s[8:9], s39, v52
	s_nop 1
	v_cndmask_b32_e64 v52, v52, v53, s[8:9]
	v_rsq_f32_e32 v52, v52
	s_nop 0
	v_mul_f32_e32 v53, 0x45800000, v52
	v_cndmask_b32_e64 v52, v52, v53, s[8:9]
	v_pk_mul_f32 v[56:57], v[46:47], v[52:53] op_sel_hi:[1,0]
	v_pk_mul_f32 v[54:55], v[44:45], v[52:53] op_sel_hi:[1,0]
	v_pk_mul_f32 v[46:47], v[42:43], v[52:53] op_sel_hi:[1,0]
	v_pk_mul_f32 v[44:45], v[40:41], v[52:53] op_sel_hi:[1,0]
	s_cbranch_vccnz .LBB0_379
	v_mul_f32_e32 v42, 0x3d122279, v55
	v_fmaak_f32 v42, v55, v42, 0x3f4c422a
	v_mul_f32_e32 v42, v55, v42
	v_mul_f32_e32 v41, 0x3d122279, v44
	v_mul_f32_e32 v42, 0xc038aa3b, v42
	v_fmaak_f32 v41, v44, v41, 0x3f4c422a
	v_exp_f32_e32 v43, v42
	v_mul_f32_e32 v42, 0x3d122279, v45
	v_mul_f32_e32 v41, v44, v41
	v_fmaak_f32 v42, v45, v42, 0x3f4c422a
	v_mul_f32_e32 v41, 0xc038aa3b, v41
	v_mul_f32_e32 v42, v45, v42
	v_exp_f32_e32 v41, v41
	v_mul_f32_e32 v42, 0xc038aa3b, v42
	v_exp_f32_e32 v53, v42
	v_mul_f32_e32 v58, 0x3d122279, v46
	v_add_f32_e32 v41, 1.0, v41
	v_rcp_f32_e32 v42, v41
	v_add_f32_e32 v41, 1.0, v43
	v_add_f32_e32 v43, 1.0, v53
	v_mul_f32_e32 v53, 0x3d122279, v56
	v_fmaak_f32 v53, v56, v53, 0x3f4c422a
	v_mul_f32_e32 v53, v56, v53
	v_fmaak_f32 v58, v46, v58, 0x3f4c422a
	v_mul_f32_e32 v53, 0xc038aa3b, v53
	v_mul_f32_e32 v58, v46, v58
	v_exp_f32_e32 v53, v53
	v_mul_f32_e32 v58, 0xc038aa3b, v58
	v_exp_f32_e32 v59, v58
	v_mul_f32_e32 v40, 0x3d122279, v54
	v_add_f32_e32 v53, 1.0, v53
	v_rcp_f32_e32 v58, v53
	v_add_f32_e32 v53, 1.0, v59
	v_mul_f32_e32 v59, 0x3d122279, v57
	v_fmaak_f32 v59, v57, v59, 0x3f4c422a
	v_mul_f32_e32 v60, 0x3d122279, v47
	v_fmaak_f32 v40, v54, v40, 0x3f4c422a
	v_mul_f32_e32 v59, v57, v59
	v_fmaak_f32 v60, v47, v60, 0x3f4c422a
	v_mul_f32_e32 v40, v54, v40
	v_mul_f32_e32 v59, 0xc038aa3b, v59
	v_mul_f32_e32 v60, v47, v60
	v_mul_f32_e32 v40, 0xc038aa3b, v40
	v_exp_f32_e32 v59, v59
	v_mul_f32_e32 v60, 0xc038aa3b, v60
	v_exp_f32_e32 v40, v40
	v_exp_f32_e32 v61, v60
	v_rcp_f32_e32 v60, v53
	v_add_f32_e32 v53, 1.0, v59
	v_add_f32_e32 v40, 1.0, v40
	v_rcp_f32_e32 v43, v43
	v_rcp_f32_e32 v59, v53
	v_add_f32_e32 v53, 1.0, v61
	v_rcp_f32_e32 v40, v40
	v_rcp_f32_e32 v41, v41
	v_rcp_f32_e32 v61, v53
	v_pk_mul_f32 v[44:45], v[44:45], v[42:43]
	v_pk_mul_f32 v[56:57], v[56:57], v[58:59]
	v_pk_mul_f32 v[54:55], v[54:55], v[40:41]
	v_pk_mul_f32 v[40:41], v[44:45], v[44:45]
	v_pk_mul_f32 v[46:47], v[46:47], v[60:61]
	v_pk_fma_f32 v[40:41], v[54:55], v[54:55], v[40:41]
	v_pk_mul_f32 v[42:43], v[46:47], v[46:47]
	v_add_f32_e32 v40, v40, v41
	v_pk_fma_f32 v[42:43], v[56:57], v[56:57], v[42:43]
	s_nop 0
	v_add_f32_e32 v40, v42, v40
	v_add_f32_e32 v58, v43, v40

; __device__ __forceinline__ float row_rstd(const float* rss, long row, int fq) {
;     const f32x4 p = *(const f32x4*)(rss + row * 16 + fq * 4); float s = (p[0] + p[1]) + (p[2] + p[3]); s += __shfl_xor(s, 16); s += __shfl_xor(s, 32);
;     return rsqrtf(s * (1.0f / 1024.0f) + 1e-6f);
;     __device__ __forceinline__ void operator()(const f32x4 (&acc)[2][2][4][2], const Unit& u, int wr, int wc, int fr, int fq) const {
;     ...
;             for (int m = 0; m < 4; ++m) { const int row = row0 + ai * HALF + m * 16; bf16_t* rowp = base + (size_t)row * 1024 + col0; float ss = 0.f; const float rn = row_rstd(rss, row, fq);
; #pragma unroll
;                 for (int bj = 0; bj < 2; ++bj) { f32x4 v0 = acc[ai][bj][m][0] * rn, v1 = acc[ai][bj][m][1] * rn;
;                     if (t <= 1) {
; #pragma unroll
;                         for (int j = 0; j < 4; ++j) { v0[j] = gelu_t(v0[j]); v1[j] = gelu_t(v1[j]); }
; #pragma unroll
;                         for (int j = 0; j < 4; ++j) ss += v0[j] * v0[j] + v1[j] * v1[j];
.LBB0_385:
	s_nop 0
	v_add_u32_e32 v34, 0xa0, v142
	v_ashrrev_i32_e32 v35, 31, v34
	s_waitcnt lgkmcnt(0)
	v_lshlrev_b64 v[32:33], 6, v[34:35]
	s_and_b64 vcc, exec, s[4:5]
	v_mov_b32_e32 v42, 0
	s_waitcnt vmcnt(13)
	v_mov_b32_e32 v40, v185
	v_mov_b32_e32 v41, v186
	v_mov_b32_e32 v37, v187
	v_mov_b32_e32 v36, v184
	v_pk_add_f32 v[36:37], v[40:41], v[36:37]
	s_nop 0
	v_add_f32_e32 v36, v36, v37
	v_mov_b32_e32 v37, v36
	s_nop 1
	v_permlane16_swap_b32_e32 v36, v37
	s_waitcnt lgkmcnt(0)
	v_add_f32_e32 v36, v36, v37
	v_mov_b32_e32 v37, v36
	s_nop 1
	v_permlane32_swap_b32_e32 v36, v37
	s_waitcnt lgkmcnt(0)
	v_add_f32_e32 v36, v36, v37
	v_fmamk_f32 v36, v36, 0x3a800000, v210
	v_mul_f32_e32 v37, 0x4b800000, v36
	v_cmp_gt_f32_e64 s[8:9], s39, v36
	s_nop 1
	v_cndmask_b32_e64 v36, v36, v37, s[8:9]
	v_rsq_f32_e32 v36, v36
	s_nop 0
	v_mul_f32_e32 v37, 0x45800000, v36
	v_cndmask_b32_e64 v36, v36, v37, s[8:9]
	v_pk_mul_f32 v[40:41], v[30:31], v[36:37] op_sel_hi:[1,0]
	v_pk_mul_f32 v[38:39], v[28:29], v[36:37] op_sel_hi:[1,0]
	v_pk_mul_f32 v[30:31], v[26:27], v[36:37] op_sel_hi:[1,0]
	v_pk_mul_f32 v[28:29], v[24:25], v[36:37] op_sel_hi:[1,0]
	s_cbranch_vccnz .LBB0_387
	v_mul_f32_e32 v26, 0x3d122279, v39
	v_fmaak_f32 v26, v39, v26, 0x3f4c422a
	v_mul_f32_e32 v26, v39, v26
	v_mul_f32_e32 v25, 0x3d122279, v28
	v_mul_f32_e32 v26, 0xc038aa3b, v26
	v_fmaak_f32 v25, v28, v25, 0x3f4c422a
	v_exp_f32_e32 v27, v26
	v_mul_f32_e32 v26, 0x3d122279, v29
	v_mul_f32_e32 v25, v28, v25
	v_fmaak_f32 v26, v29, v26, 0x3f4c422a
	v_mul_f32_e32 v25, 0xc038aa3b, v25
	v_mul_f32_e32 v26, v29, v26
	v_exp_f32_e32 v25, v25
	v_mul_f32_e32 v26, 0xc038aa3b, v26
	v_exp_f32_e32 v37, v26
	v_mul_f32_e32 v42, 0x3d122279, v30
	v_add_f32_e32 v25, 1.0, v25
	v_rcp_f32_e32 v26, v25
	v_add_f32_e32 v25, 1.0, v27
	v_add_f32_e32 v27, 1.0, v37
	v_mul_f32_e32 v37, 0x3d122279, v40
	v_fmaak_f32 v37, v40, v37, 0x3f4c422a
	v_mul_f32_e32 v37, v40, v37
	v_fmaak_f32 v42, v30, v42, 0x3f4c422a
	v_mul_f32_e32 v37, 0xc038aa3b, v37
	v_mul_f32_e32 v42, v30, v42
	v_exp_f32_e32 v37, v37
	v_mul_f32_e32 v42, 0xc038aa3b, v42
	v_exp_f32_e32 v43, v42
	v_mul_f32_e32 v24, 0x3d122279, v38
	v_add_f32_e32 v37, 1.0, v37
	v_rcp_f32_e32 v42, v37
	v_add_f32_e32 v37, 1.0, v43
	v_mul_f32_e32 v43, 0x3d122279, v41
	v_fmaak_f32 v43, v41, v43, 0x3f4c422a
	v_mul_f32_e32 v44, 0x3d122279, v31
	v_fmaak_f32 v24, v38, v24, 0x3f4c422a
	v_mul_f32_e32 v43, v41, v43
	v_fmaak_f32 v44, v31, v44, 0x3f4c422a
	v_mul_f32_e32 v24, v38, v24
	v_mul_f32_e32 v43, 0xc038aa3b, v43
	v_mul_f32_e32 v44, v31, v44
	v_mul_f32_e32 v24, 0xc038aa3b, v24
	v_exp_f32_e32 v43, v43
	v_mul_f32_e32 v44, 0xc038aa3b, v44
	v_exp_f32_e32 v24, v24
	v_exp_f32_e32 v45, v44
	v_rcp_f32_e32 v44, v37
	v_add_f32_e32 v37, 1.0, v43
	v_add_f32_e32 v24, 1.0, v24
	v_rcp_f32_e32 v27, v27
	v_rcp_f32_e32 v43, v37
	v_add_f32_e32 v37, 1.0, v45
	v_rcp_f32_e32 v24, v24
	v_rcp_f32_e32 v25, v25
	v_rcp_f32_e32 v45, v37
	v_pk_mul_f32 v[28:29], v[28:29], v[26:27]
	v_pk_mul_f32 v[40:41], v[40:41], v[42:43]
	v_pk_mul_f32 v[38:39], v[38:39], v[24:25]
	v_pk_mul_f32 v[24:25], v[28:29], v[28:29]
	v_pk_mul_f32 v[30:31], v[30:31], v[44:45]
	v_pk_fma_f32 v[24:25], v[38:39], v[38:39], v[24:25]
	v_pk_mul_f32 v[26:27], v[30:31], v[30:31]
	v_add_f32_e32 v24, v24, v25
	v_pk_fma_f32 v[26:27], v[40:41], v[40:41], v[26:27]
	s_nop 0
	v_add_f32_e32 v24, v26, v24
	v_add_f32_e32 v42, v27, v24

; __device__ __forceinline__ float row_rstd(const float* rss, long row, int fq) {
;     const f32x4 p = *(const f32x4*)(rss + row * 16 + fq * 4); float s = (p[0] + p[1]) + (p[2] + p[3]); s += __shfl_xor(s, 16); s += __shfl_xor(s, 32);
;     return rsqrtf(s * (1.0f / 1024.0f) + 1e-6f);
;     __device__ __forceinline__ void operator()(const f32x4 (&acc)[2][2][4][2], const Unit& u, int wr, int wc, int fr, int fq) const {
;     ...
;             for (int m = 0; m < 4; ++m) { const int row = row0 + ai * HALF + m * 16; bf16_t* rowp = base + (size_t)row * 1024 + col0; float ss = 0.f; const float rn = row_rstd(rss, row, fq);
; #pragma unroll
;                 for (int bj = 0; bj < 2; ++bj) { f32x4 v0 = acc[ai][bj][m][0] * rn, v1 = acc[ai][bj][m][1] * rn;
;                     if (t <= 1) {
; #pragma unroll
;                         for (int j = 0; j < 4; ++j) { v0[j] = gelu_t(v0[j]); v1[j] = gelu_t(v1[j]); }
; #pragma unroll
;                         for (int j = 0; j < 4; ++j) ss += v0[j] * v0[j] + v1[j] * v1[j];
.LBB0_393:
	s_nop 0
	v_add_u32_e32 v18, 0xb0, v142
	v_ashrrev_i32_e32 v19, 31, v18
	s_waitcnt lgkmcnt(0)
	v_lshlrev_b64 v[16:17], 6, v[18:19]
	s_and_b64 vcc, exec, s[4:5]
	v_mov_b32_e32 v26, 0
	s_waitcnt vmcnt(14)
	v_mov_b32_e32 v24, v189
	v_mov_b32_e32 v25, v190
	v_mov_b32_e32 v21, v191
	v_mov_b32_e32 v20, v188
	v_pk_add_f32 v[20:21], v[24:25], v[20:21]
	s_nop 0
	v_add_f32_e32 v20, v20, v21
	v_mov_b32_e32 v21, v20
	s_nop 1
	v_permlane16_swap_b32_e32 v20, v21
	s_waitcnt lgkmcnt(0)
	v_add_f32_e32 v20, v20, v21
	v_mov_b32_e32 v21, v20
	s_nop 1
	v_permlane32_swap_b32_e32 v20, v21
	s_waitcnt lgkmcnt(0)
	v_add_f32_e32 v20, v20, v21
	v_fmamk_f32 v20, v20, 0x3a800000, v210
	v_mul_f32_e32 v21, 0x4b800000, v20
	v_cmp_gt_f32_e64 s[8:9], s39, v20
	s_nop 1
	v_cndmask_b32_e64 v20, v20, v21, s[8:9]
	v_rsq_f32_e32 v20, v20
	s_nop 0
	v_mul_f32_e32 v21, 0x45800000, v20
	v_cndmask_b32_e64 v20, v20, v21, s[8:9]
	v_pk_mul_f32 v[24:25], v[14:15], v[20:21] op_sel_hi:[1,0]
	v_pk_mul_f32 v[22:23], v[12:13], v[20:21] op_sel_hi:[1,0]
	v_pk_mul_f32 v[14:15], v[10:11], v[20:21] op_sel_hi:[1,0]
	v_pk_mul_f32 v[12:13], v[8:9], v[20:21] op_sel_hi:[1,0]
	s_cbranch_vccnz .LBB0_395
	v_mul_f32_e32 v10, 0x3d122279, v23
	v_fmaak_f32 v10, v23, v10, 0x3f4c422a
	v_mul_f32_e32 v10, v23, v10
	v_mul_f32_e32 v9, 0x3d122279, v12
	v_mul_f32_e32 v10, 0xc038aa3b, v10
	v_fmaak_f32 v9, v12, v9, 0x3f4c422a
	v_exp_f32_e32 v11, v10
	v_mul_f32_e32 v10, 0x3d122279, v13
	v_mul_f32_e32 v9, v12, v9
	v_fmaak_f32 v10, v13, v10, 0x3f4c422a
	v_mul_f32_e32 v9, 0xc038aa3b, v9
	v_mul_f32_e32 v10, v13, v10
	v_exp_f32_e32 v9, v9
	v_mul_f32_e32 v10, 0xc038aa3b, v10
	v_exp_f32_e32 v21, v10
	v_mul_f32_e32 v26, 0x3d122279, v14
	v_add_f32_e32 v9, 1.0, v9
	v_rcp_f32_e32 v10, v9
	v_add_f32_e32 v9, 1.0, v11
	v_add_f32_e32 v11, 1.0, v21
	v_mul_f32_e32 v21, 0x3d122279, v24
	v_fmaak_f32 v21, v24, v21, 0x3f4c422a
	v_mul_f32_e32 v21, v24, v21
	v_fmaak_f32 v26, v14, v26, 0x3f4c422a
	v_mul_f32_e32 v21, 0xc038aa3b, v21
	v_mul_f32_e32 v26, v14, v26
	v_exp_f32_e32 v21, v21
	v_mul_f32_e32 v26, 0xc038aa3b, v26
	v_exp_f32_e32 v27, v26
	v_mul_f32_e32 v8, 0x3d122279, v22
	v_add_f32_e32 v21, 1.0, v21
	v_rcp_f32_e32 v26, v21
	v_add_f32_e32 v21, 1.0, v27
	v_mul_f32_e32 v27, 0x3d122279, v25
	v_fmaak_f32 v27, v25, v27, 0x3f4c422a
	v_mul_f32_e32 v28, 0x3d122279, v15
	v_fmaak_f32 v8, v22, v8, 0x3f4c422a
	v_mul_f32_e32 v27, v25, v27
	v_fmaak_f32 v28, v15, v28, 0x3f4c422a
	v_mul_f32_e32 v8, v22, v8
	v_mul_f32_e32 v27, 0xc038aa3b, v27
	v_mul_f32_e32 v28, v15, v28
	v_mul_f32_e32 v8, 0xc038aa3b, v8
	v_exp_f32_e32 v27, v27
	v_mul_f32_e32 v28, 0xc038aa3b, v28
	v_exp_f32_e32 v8, v8
	v_exp_f32_e32 v29, v28
	v_rcp_f32_e32 v28, v21
	v_add_f32_e32 v21, 1.0, v27
	v_add_f32_e32 v8, 1.0, v8
	v_rcp_f32_e32 v11, v11
	v_rcp_f32_e32 v27, v21
	v_add_f32_e32 v21, 1.0, v29
	v_rcp_f32_e32 v8, v8
	v_rcp_f32_e32 v9, v9
	v_rcp_f32_e32 v29, v21
	v_pk_mul_f32 v[12:13], v[12:13], v[10:11]
	v_pk_mul_f32 v[24:25], v[24:25], v[26:27]
	v_pk_mul_f32 v[22:23], v[22:23], v[8:9]
	v_pk_mul_f32 v[8:9], v[12:13], v[12:13]
	v_pk_mul_f32 v[14:15], v[14:15], v[28:29]
	v_pk_fma_f32 v[8:9], v[22:23], v[22:23], v[8:9]
	v_pk_mul_f32 v[10:11], v[14:15], v[14:15]
	v_add_f32_e32 v8, v8, v9
	v_pk_fma_f32 v[10:11], v[24:25], v[24:25], v[10:11]
	s_nop 0
	v_add_f32_e32 v8, v10, v8
	v_add_f32_e32 v26, v11, v8
